# EW residual phases: all 12 row loads issued at the top of each row iteration (counted waits), instead of 2-3 dependent load groups
# speedup vs baseline: 1.0726x; 1.0254x over previous
; __device__ __forceinline__ float bf_lo(unsigned w) { return __uint_as_float(w << 16); }
; __device__ __forceinline__ float bf_hi(unsigned w) { return __uint_as_float(w & 0xffff0000u); }
; __device__ __forceinline__ void ew_phase(const Frame& F, const bf16_t* f, const float* gpost, float alpha, const float* hin, float* hout, const float* gpre, bf16_t* xn, ...
;     ...
;     for (int it_ = 0; it_ < it_n; ++it_) {
;         const int m = prow0 >= 0 ? prow0 + F.wave * 8 + it_ : F.gw + it_ * F.NGW; if (m >= T) break;
;         const u32x2* fr = (const u32x2*)(f + (size_t)m * DM) + F.lane; const f32x4* hr = (const f32x4*)(hin + (size_t)m * DM) + F.lane;
;         f32x4 fv[4], hv[4]; float s = 0.f;
; #pragma unroll
;         for (int j = 0; j < 4; ++j) { const u32x2 w = fr[64 * j]; hv[j] = in24 ? load24(h24 + (size_t)m * (DM * 3), F.lane + 64 * j) : hr[64 * j]; fv[j] = (f32x4){bf_lo(w.x), bf_hi(w.x), bf_lo(w.y), bf_hi(w.y)};
;             s += (fv[j].x * fv[j].x + fv[j].y * fv[j].y) + (fv[j].z * fv[j].z + fv[j].w * fv[j].w); }
;         const float rstd = alpha / sqrtf(wave_sum(s) * (1.f / DM) + RMS_EPS);
.LBB0_209:
	v_readlane_b32 s0, v252, 11
	s_add_i32 s2, s14, s9
	v_readlane_b32 s1, v252, 12
	s_and_b64 s[0:1], s[0:1], exec
	s_cselect_b32 s10, s2, s15
	s_cmpk_gt_i32 s10, 0x3fff
	s_mov_b64 s[0:1], -1
	s_cbranch_scc1 .LBB0_208
	s_ashr_i32 s11, s10, 31
	s_lshl_b64 s[12:13], s[10:11], 11
	s_mul_i32 s0, s10, 0xc00
	s_mul_hi_i32 s1, s10, 0xc00
	s_add_u32 s0, s24, s0
	s_addc_u32 s1, s25, s1
	v_lshl_add_u64 v[70:71], v[34:35], 0, s[12:13]
	v_lshl_add_u64 v[54:55], s[0:1], 0, v[38:39]
	v_lshl_add_u64 v[64:65], s[0:1], 0, v[40:41]
	v_lshl_add_u64 v[162:163], s[0:1], 0, v[44:45]
	v_lshl_add_u64 v[164:165], s[0:1], 0, v[46:47]
	global_load_dwordx2 v[62:63], v[70:71], off
	global_load_dwordx2 v[58:59], v[54:55], off
	global_load_dwordx2 v[60:61], v[54:55], off offset:4
	global_load_dwordx2 v[72:73], v[70:71], off offset:512
	global_load_dwordx2 v[68:69], v[64:65], off
	global_load_dwordx2 v[74:75], v[64:65], off offset:4
	global_load_dwordx2 v[78:79], v[70:71], off offset:1024
	global_load_dwordx2 v[82:83], v[162:163], off
	global_load_dwordx2 v[84:85], v[162:163], off offset:4
	global_load_dwordx2 v[86:87], v[70:71], off offset:1536
	global_load_dwordx2 v[166:167], v[164:165], off
	global_load_dwordx2 v[88:89], v[164:165], off offset:4
	s_mov_b32 s2, 0xff00
	s_waitcnt vmcnt(10)
	v_lshrrev_b32_e32 v59, 8, v59
	s_waitcnt vmcnt(9) lgkmcnt(0)
	v_lshlrev_b32_e32 v0, 24, v61
	v_lshlrev_b32_e32 v57, 16, v60
	v_and_b32_e32 v59, 0xffff00, v59
	v_and_b32_sdwa v60, v58, s2 dst_sel:DWORD dst_unused:UNUSED_PAD src0_sel:WORD_1 src1_sel:DWORD
	v_lshlrev_b32_e32 v56, 8, v58
	v_or_b32_e32 v58, v0, v59
	v_or_b32_e32 v57, v57, v60
	v_and_b32_e32 v59, 0xffffff00, v61
	v_lshlrev_b32_e32 v60, 16, v62
	v_and_b32_e32 v61, 0xffff0000, v62
	v_lshlrev_b32_e32 v62, 16, v63
	v_and_b32_e32 v63, 0xffff0000, v63
	v_mul_f32_e32 v0, v63, v63
	s_waitcnt vmcnt(7)
	v_lshrrev_b32_e32 v69, 8, v69
	v_pk_fma_f32 v[96:97], v[62:63], v[62:63], v[0:1] op_sel_hi:[1,1,0]
	s_waitcnt vmcnt(6)
	v_lshlrev_b32_e32 v0, 24, v75
	v_lshlrev_b32_e32 v67, 16, v74
	v_and_b32_e32 v69, 0xffff00, v69
	v_and_b32_sdwa v74, v68, s2 dst_sel:DWORD dst_unused:UNUSED_PAD src0_sel:WORD_1 src1_sel:DWORD
	v_lshlrev_b32_e32 v66, 8, v68
	v_or_b32_e32 v68, v0, v69
	v_or_b32_e32 v67, v67, v74
	v_and_b32_e32 v69, 0xffffff00, v75
	v_lshlrev_b32_e32 v75, 16, v73
	v_lshlrev_b32_e32 v74, 16, v72
	v_and_b32_e32 v73, 0xffff0000, v73
	v_and_b32_e32 v72, 0xffff0000, v72
	v_pk_mul_f32 v[76:77], v[72:73], v[72:73]
	s_waitcnt vmcnt(5)
	v_lshlrev_b32_e32 v92, 16, v78
	v_pk_fma_f32 v[100:101], v[74:75], v[74:75], v[76:77]
	v_lshl_add_u64 v[76:77], s[0:1], 0, v[44:45]
	v_lshl_add_u64 v[70:71], s[0:1], 0, v[46:47]
	v_and_b32_e32 v93, 0xffff0000, v78
	v_lshlrev_b32_e32 v94, 16, v79
	v_and_b32_e32 v95, 0xffff0000, v79
	v_mov_b32_e32 v104, v96
	v_pk_add_f32 v[100:101], v[100:101], v[100:101] op_sel:[0,1] op_sel_hi:[1,0]
	s_waitcnt vmcnt(4)
	v_lshrrev_b32_e32 v83, 8, v83
	v_lshlrev_b32_e32 v80, 8, v82
	s_waitcnt vmcnt(3)
	v_lshlrev_b32_e32 v0, 24, v85
	v_lshlrev_b32_e32 v81, 16, v84
	v_and_b32_e32 v83, 0xffff00, v83
	v_and_b32_sdwa v82, v82, s2 dst_sel:DWORD dst_unused:UNUSED_PAD src0_sel:WORD_1 src1_sel:DWORD
	v_or_b32_e32 v84, v0, v83
	v_or_b32_e32 v81, v81, v82
	s_waitcnt vmcnt(2)
	v_lshlrev_b32_e32 v91, 16, v86
	v_mov_b32_e32 v105, v91
	v_and_b32_e32 v85, 0xffffff00, v85
	s_waitcnt vmcnt(1)
	v_lshrrev_b32_e32 v83, 8, v167
	s_waitcnt vmcnt(0)
	v_lshlrev_b32_e32 v0, 24, v89
	v_and_b32_e32 v83, 0xffff00, v83
	v_lshlrev_b32_e32 v78, 8, v166
	v_lshlrev_b32_e32 v79, 16, v88
	v_and_b32_sdwa v88, v166, s2 dst_sel:DWORD dst_unused:UNUSED_PAD src0_sel:WORD_1 src1_sel:DWORD
	v_or_b32_e32 v82, v0, v83
	v_mul_f32_e32 v0, v61, v61
	v_pk_fma_f32 v[102:103], v[60:61], v[60:61], v[0:1] op_sel_hi:[1,1,0]
	v_and_b32_e32 v83, 0xffffff00, v89
	v_and_b32_e32 v89, 0xffff0000, v86
	v_mov_b32_e32 v90, v102
	v_or_b32_e32 v79, v79, v88
	v_mul_f32_e32 v88, v89, v89
	v_pk_add_f32 v[96:97], v[102:103], v[96:97]
	v_pk_mul_f32 v[102:103], v[90:91], v[104:105]
	v_mov_b32_e32 v101, v88
	v_mov_b32_e32 v97, v103
	v_mul_f32_e32 v0, v93, v93
	v_lshlrev_b32_e32 v86, 16, v87
	v_and_b32_e32 v87, 0xffff0000, v87
	v_pk_add_f32 v[96:97], v[96:97], v[100:101]
	v_pk_fma_f32 v[100:101], v[92:93], v[92:93], v[0:1] op_sel_hi:[1,1,0]
	v_mul_f32_e32 v0, v95, v95
	v_mul_f32_e32 v99, v86, v86
	v_mul_f32_e32 v106, v87, v87
	v_pk_fma_f32 v[102:103], v[94:95], v[94:95], v[0:1] op_sel_hi:[1,1,0]
	v_mov_b32_e32 v101, v99
	v_mov_b32_e32 v103, v106
	v_pk_add_f32 v[100:101], v[100:101], v[102:103]
	v_and_b32_e32 v0, 64, v230
	v_pk_add_f32 v[96:97], v[96:97], v[100:101]
	v_add_u32_e32 v100, 64, v0
	v_xor_b32_e32 v0, 1, v230
	v_cmp_lt_i32_e32 vcc, v0, v100
	v_add_f32_e32 v88, v96, v97
	s_mov_b32 s2, 0xf800000
	v_cndmask_b32_e32 v0, v230, v0, vcc
	v_lshlrev_b32_e32 v0, 2, v0
	ds_bpermute_b32 v90, v0, v88
	s_waitcnt lgkmcnt(0)
	v_add_f32_e32 v88, v88, v90
	v_xor_b32_e32 v90, 2, v230
	v_cmp_lt_i32_e32 vcc, v90, v100
	s_nop 1
	v_cndmask_b32_e32 v90, v230, v90, vcc
	v_lshlrev_b32_e32 v90, 2, v90
	ds_bpermute_b32 v96, v90, v88
	s_waitcnt lgkmcnt(0)
	v_add_f32_e32 v88, v88, v96
	v_xor_b32_e32 v96, 4, v230
	v_cmp_lt_i32_e32 vcc, v96, v100
	s_nop 1
	v_cndmask_b32_e32 v96, v230, v96, vcc
	v_lshlrev_b32_e32 v96, 2, v96
	ds_bpermute_b32 v97, v96, v88
	s_waitcnt lgkmcnt(0)
	v_add_f32_e32 v88, v88, v97
	v_xor_b32_e32 v97, 8, v230
	v_cmp_lt_i32_e32 vcc, v97, v100
	s_nop 1
	v_cndmask_b32_e32 v97, v230, v97, vcc
	v_lshlrev_b32_e32 v97, 2, v97
	ds_bpermute_b32 v99, v97, v88
	s_waitcnt lgkmcnt(0)
	v_add_f32_e32 v88, v88, v99
	v_xor_b32_e32 v99, 16, v230
	v_cmp_lt_i32_e32 vcc, v99, v100
	s_nop 1
	v_cndmask_b32_e32 v99, v230, v99, vcc
	v_lshlrev_b32_e32 v99, 2, v99
	ds_bpermute_b32 v101, v99, v88
	s_waitcnt lgkmcnt(0)
; __device__ __forceinline__ void ew_phase(const Frame& F, const bf16_t* f, const float* gpost, float alpha, const float* hin, float* hout, const float* gpre, bf16_t* xn, ...
;     ...
;         const float rstd = alpha / sqrtf(wave_sum(s) * (1.f / DM) + RMS_EPS);
;         float s2 = 0.f; f32x4* ho = (f32x4*)(hout + (size_t)m * DM) + F.lane;
; #pragma unroll
;         for (int j = 0; j < 4; ++j) { hv[j] = hv[j] + fv[j] * rstd * gp[j]; if (out24) store24(h24 + (size_t)m * (DM * 3), F.lane + 64 * j, hv[j]); else ho[64 * j] = hv[j]; s2 += (hv[j].x * hv[j].x + hv[j].y * hv[j].y) + (hv[j].z * hv[j].z + hv[j].w * hv[j].w); }
;         if (gpre) {
;             const float r2 = 1.0f / sqrtf(wave_sum(s2) * (1.f / DM) + RMS_EPS);
	v_add_f32_e32 v88, v88, v101
	v_xor_b32_e32 v101, 32, v230
	v_cmp_lt_i32_e32 vcc, v101, v100
	s_nop 1
	v_cndmask_b32_e32 v100, v230, v101, vcc
	v_lshlrev_b32_e32 v100, 2, v100
	ds_bpermute_b32 v101, v100, v88
	s_waitcnt lgkmcnt(0)
	v_add_f32_e32 v88, v88, v101
	v_fmamk_f32 v88, v88, 0x3a800000, v225
	v_cmp_gt_f32_e32 vcc, s2, v88
	v_mul_f32_e32 v101, 0x4f800000, v88
	s_nop 0
	v_cndmask_b32_e32 v88, v88, v101, vcc
	v_sqrt_f32_e32 v101, v88
	s_nop 0
	v_add_u32_e32 v102, -1, v101
	v_fma_f32 v103, -v102, v101, v88
	v_cmp_ge_f32_e64 s[0:1], 0, v103
	v_add_u32_e32 v103, 1, v101
	s_nop 0
	v_cndmask_b32_e64 v102, v101, v102, s[0:1]
	v_fma_f32 v101, -v103, v101, v88
	v_cmp_lt_f32_e64 s[0:1], 0, v101
	s_nop 1
	v_cndmask_b32_e64 v101, v102, v103, s[0:1]
	v_mul_f32_e32 v102, 0x37800000, v101
	v_cndmask_b32_e32 v101, v101, v102, vcc
	v_cmp_class_f32_e32 vcc, v88, v226
	s_nop 1
	v_cndmask_b32_e32 v88, v101, v88, vcc
	v_div_scale_f32 v101, s[0:1], v88, v88, 0.5
	v_rcp_f32_e32 v102, v101
	s_movk_i32 s0, 0x7f
	s_mov_b32 s1, 0x7060503
	v_fma_f32 v103, -v101, v102, 1.0
	v_fmac_f32_e32 v102, v103, v102
	v_div_scale_f32 v103, vcc, 0.5, v88, 0.5
	v_mul_f32_e32 v104, v103, v102
	v_fma_f32 v105, -v101, v104, v103
	v_fmac_f32_e32 v104, v105, v102
	v_fma_f32 v101, -v101, v104, v103
	v_div_fmas_f32 v101, v101, v102, v104
	v_div_fixup_f32 v102, v101, v88, 0.5
	v_pk_mul_f32 v[60:61], v[102:103], v[60:61] op_sel_hi:[0,1]
	v_pk_mul_f32 v[62:63], v[102:103], v[62:63] op_sel_hi:[0,1]
	v_pk_fma_f32 v[58:59], v[4:5], v[62:63], v[58:59]
	v_pk_fma_f32 v[56:57], v[2:3], v[60:61], v[56:57]
	v_bfe_u32 v63, v58, 8, 1
	v_bfe_u32 v61, v57, 8, 1
	v_bfe_u32 v60, v56, 8, 1
	v_add3_u32 v61, v57, v61, s0
	v_add3_u32 v63, v58, v63, s0
	v_bfe_u32 v101, v59, 8, 1
	v_add3_u32 v60, v56, v60, s0
	v_lshrrev_b32_e32 v62, 8, v61
	v_lshrrev_b32_e32 v88, 8, v63
	v_add3_u32 v101, v59, v101, s0
	v_alignbit_b32 v60, v62, v60, 8
	v_alignbit_b32 v61, v88, v61, 16
	v_perm_b32 v62, v101, v63, s1
	global_store_dwordx3 v[54:55], v[60:62], off
	v_pk_mul_f32 v[54:55], v[58:59], v[58:59]
	v_mov_b32_e32 v88, v91
	v_pk_mul_f32 v[60:61], v[56:57], v[56:57]
	s_nop 0
	v_pk_mov_b32 v[62:63], v[60:61], v[54:55] op_sel:[1,0]
	v_mov_b32_e32 v61, v55
	v_pk_add_f32 v[54:55], v[60:61], v[62:63]
	s_nop 0
	v_pk_add_f32 v[62:63], v[54:55], v[54:55] op_sel_hi:[0,1]
	v_mov_b32_e32 v54, v74
	v_mov_b32_e32 v55, v72
	v_mov_b32_e32 v72, v75
	v_pk_mul_f32 v[60:61], v[102:103], v[54:55] op_sel_hi:[0,1]
	v_pk_mul_f32 v[54:55], v[102:103], v[72:73] op_sel_hi:[0,1]
	v_pk_fma_f32 v[54:55], v[8:9], v[54:55], v[68:69]
	v_pk_fma_f32 v[60:61], v[6:7], v[60:61], v[66:67]
	v_bfe_u32 v68, v54, 8, 1
	v_bfe_u32 v66, v61, 8, 1
	v_bfe_u32 v62, v60, 8, 1
	v_add3_u32 v67, v61, v66, s0
	v_add3_u32 v68, v54, v68, s0
	v_bfe_u32 v72, v55, 8, 1
	v_add3_u32 v62, v60, v62, s0
	v_lshrrev_b32_e32 v66, 8, v67
	v_lshrrev_b32_e32 v69, 8, v68
	v_add3_u32 v72, v55, v72, s0
	v_alignbit_b32 v66, v66, v62, 8
	v_alignbit_b32 v67, v69, v67, 16
	v_perm_b32 v68, v72, v68, s1
	global_store_dwordx3 v[64:65], v[66:68], off
	v_pk_mul_f32 v[64:65], v[54:55], v[54:55]
	s_nop 0
	v_pk_mul_f32 v[66:67], v[60:61], v[60:61]
	s_nop 0
	v_pk_mov_b32 v[68:69], v[66:67], v[64:65] op_sel:[1,0]
	v_mov_b32_e32 v67, v65
	v_pk_add_f32 v[64:65], v[66:67], v[68:69]
	v_pk_mul_f32 v[66:67], v[102:103], v[92:93] op_sel_hi:[0,1]
	v_pk_add_f32 v[68:69], v[64:65], v[64:65] op_sel_hi:[0,1]
	v_pk_mul_f32 v[64:65], v[102:103], v[94:95] op_sel_hi:[0,1]
	v_pk_fma_f32 v[64:65], v[20:21], v[64:65], v[84:85]
	v_pk_fma_f32 v[72:73], v[18:19], v[66:67], v[80:81]
	v_bfe_u32 v68, v64, 8, 1
	v_bfe_u32 v66, v73, 8, 1
	v_bfe_u32 v62, v72, 8, 1
	v_add3_u32 v67, v73, v66, s0
	v_add3_u32 v68, v64, v68, s0
	v_bfe_u32 v75, v65, 8, 1
	v_add3_u32 v62, v72, v62, s0
	v_lshrrev_b32_e32 v66, 8, v67
	v_lshrrev_b32_e32 v74, 8, v68
	v_add3_u32 v75, v65, v75, s0
	v_alignbit_b32 v66, v66, v62, 8
	v_alignbit_b32 v67, v74, v67, 16
	v_perm_b32 v68, v75, v68, s1
	global_store_dwordx3 v[76:77], v[66:68], off
	v_pk_mul_f32 v[74:75], v[86:87], v[102:103] op_sel_hi:[1,0]
	v_mul_f32_e32 v62, v72, v72
	v_pk_mul_f32 v[66:67], v[88:89], v[102:103] op_sel_hi:[1,0]
	v_pk_fma_f32 v[74:75], v[24:25], v[74:75], v[82:83]
	v_pk_fma_f32 v[76:77], v[22:23], v[66:67], v[78:79]
	v_pk_fma_f32 v[80:81], v[72:73], v[72:73], v[62:63] op_sel_hi:[1,1,0]
	v_mul_f32_e32 v62, v64, v64
	v_bfe_u32 v66, v77, 8, 1
	v_bfe_u32 v68, v74, 8, 1
	v_pk_fma_f32 v[84:85], v[64:65], v[64:65], v[62:63] op_sel_hi:[1,1,0]
	v_bfe_u32 v62, v76, 8, 1
	v_add3_u32 v67, v77, v66, s0
	v_add3_u32 v68, v74, v68, s0
	v_bfe_u32 v79, v75, 8, 1
	v_add3_u32 v62, v76, v62, s0
	v_lshrrev_b32_e32 v66, 8, v67
	v_lshrrev_b32_e32 v78, 8, v68
	v_add3_u32 v79, v75, v79, s0
	v_alignbit_b32 v66, v66, v62, 8
	v_alignbit_b32 v67, v78, v67, 16
	v_perm_b32 v68, v79, v68, s1
	global_store_dwordx3 v[70:71], v[66:68], off
	v_mul_f32_e32 v80, v76, v76
	v_mul_f32_e32 v84, v77, v77
	v_mul_f32_e32 v62, v75, v75
	v_mul_f32_e32 v68, v74, v74
	v_pk_add_f32 v[66:67], v[80:81], v[84:85]
	v_pk_add_f32 v[62:63], v[62:63], v[68:69]
	v_lshl_add_u64 v[78:79], v[36:37], 0, s[12:13]
	v_pk_add_f32 v[62:63], v[66:67], v[62:63]
	s_nop 0
	v_add_f32_e32 v62, v62, v63
	ds_bpermute_b32 v63, v0, v62
	s_waitcnt lgkmcnt(0)
	v_add_f32_e32 v62, v62, v63
	ds_bpermute_b32 v63, v90, v62
	s_waitcnt lgkmcnt(0)
	v_add_f32_e32 v62, v62, v63
	ds_bpermute_b32 v63, v96, v62
	s_waitcnt lgkmcnt(0)
	v_add_f32_e32 v62, v62, v63
	ds_bpermute_b32 v63, v97, v62
	s_waitcnt lgkmcnt(0)
	v_add_f32_e32 v62, v62, v63
	ds_bpermute_b32 v63, v99, v62
	s_waitcnt lgkmcnt(0)
	v_add_f32_e32 v62, v62, v63
	ds_bpermute_b32 v63, v100, v62
	s_waitcnt lgkmcnt(0)
; #define LAS __attribute__((address_space(3)))
; __device__ __forceinline__ unsigned cvt_pk_bf16(float lo, float hi) { f32x2 v = {lo, hi}; bf16x2_t b = __builtin_convertvector(v, bf16x2_t); return __builtin_bit_cast(unsigned, b); }
; __device__ __forceinline__ void ew_phase(const Frame& F, const bf16_t* f, const float* gpost, float alpha, const float* hin, float* hout, const float* gpre, bf16_t* xn, ...
;     ...
;             const float r2 = 1.0f / sqrtf(wave_sum(s2) * (1.f / DM) + RMS_EPS);
;             u32x2* o8 = (u32x2*)(xn + (size_t)m * DM) + F.lane;
; #pragma unroll
;             for (int j = 0; j < 4; ++j) { hv[j] = hv[j] * r2 * gq[j]; u32x2 w; w.x = cvt_pk_bf16(hv[j].x, hv[j].y); w.y = cvt_pk_bf16(hv[j].z, hv[j].w); o8[64 * j] = w; }
;             if (win_l) {
;                 float a8[8];
; #pragma unroll
;                 for (int k = 0; k < 8; ++k) a8[k] = 0.f;
; #pragma unroll
;                 for (int k = 0; k < 8; ++k)
; #pragma unroll
;                     for (int j = 0; j < 4; ++j) { const f32x4 w4 = *(const LAS f32x4*)(WF + k * DM + 256 * j + 4 * F.lane);
;                         a8[k] += (hv[j].x * w4.x + hv[j].y * w4.y) + (hv[j].z * w4.z + hv[j].w * w4.w); }
	v_add_f32_e32 v62, v62, v63
	v_fmamk_f32 v62, v62, 0x3a800000, v225
	v_cmp_gt_f32_e32 vcc, s2, v62
	v_mul_f32_e32 v63, 0x4f800000, v62
	s_nop 0
	v_cndmask_b32_e32 v62, v62, v63, vcc
	v_sqrt_f32_e32 v63, v62
	s_nop 0
	v_add_u32_e32 v66, -1, v63
	v_fma_f32 v67, -v66, v63, v62
	v_cmp_ge_f32_e64 s[0:1], 0, v67
	v_add_u32_e32 v67, 1, v63
	s_nop 0
	v_cndmask_b32_e64 v66, v63, v66, s[0:1]
	v_fma_f32 v63, -v67, v63, v62
	v_cmp_lt_f32_e64 s[0:1], 0, v63
	s_nop 1
	v_cndmask_b32_e64 v63, v66, v67, s[0:1]
	v_mul_f32_e32 v66, 0x37800000, v63
	v_cndmask_b32_e32 v63, v63, v66, vcc
	v_cmp_class_f32_e32 vcc, v62, v226
	s_nop 1
	v_cndmask_b32_e32 v62, v63, v62, vcc
	v_div_scale_f32 v63, s[0:1], v62, v62, 1.0
	v_rcp_f32_e32 v66, v63
	s_nop 0
	v_fma_f32 v67, -v63, v66, 1.0
	v_fmac_f32_e32 v66, v67, v66
	v_div_scale_f32 v67, vcc, 1.0, v62, 1.0
	v_mul_f32_e32 v68, v67, v66
	v_fma_f32 v69, -v63, v68, v67
	v_fmac_f32_e32 v68, v69, v66
	v_fma_f32 v63, -v63, v68, v67
	v_div_fmas_f32 v63, v63, v66, v68
	v_div_fixup_f32 v70, v63, v62, 1.0
	v_pk_mul_f32 v[56:57], v[56:57], v[70:71] op_sel_hi:[1,0]
	v_pk_mul_f32 v[58:59], v[58:59], v[70:71] op_sel_hi:[1,0]
	v_pk_mul_f32 v[68:69], v[10:11], v[56:57]
	v_pk_mul_f32 v[66:67], v[12:13], v[58:59]
	v_cvt_pk_bf16_f32 v56, v68, v69
	v_cvt_pk_bf16_f32 v57, v66, v67
	global_store_dwordx2 v[78:79], v[56:57], off
	v_pk_mul_f32 v[56:57], v[60:61], v[70:71] op_sel_hi:[1,0]
	v_pk_mul_f32 v[54:55], v[54:55], v[70:71] op_sel_hi:[1,0]
	v_pk_mul_f32 v[62:63], v[14:15], v[56:57]
	v_pk_mul_f32 v[58:59], v[16:17], v[54:55]
	v_cvt_pk_bf16_f32 v54, v62, v63
	v_cvt_pk_bf16_f32 v55, v58, v59
	global_store_dwordx2 v[78:79], v[54:55], off offset:512
	v_pk_mul_f32 v[54:55], v[72:73], v[70:71] op_sel_hi:[1,0]
	v_pk_mul_f32 v[56:57], v[64:65], v[70:71] op_sel_hi:[1,0]
	v_pk_mul_f32 v[64:65], v[26:27], v[54:55]
	v_pk_mul_f32 v[60:61], v[28:29], v[56:57]
	v_cvt_pk_bf16_f32 v54, v64, v65
	v_cvt_pk_bf16_f32 v55, v60, v61
	global_store_dwordx2 v[78:79], v[54:55], off offset:1024
	v_pk_mul_f32 v[56:57], v[76:77], v[70:71] op_sel_hi:[1,0]
	v_pk_mul_f32 v[54:55], v[74:75], v[70:71] op_sel_hi:[1,0]
	v_pk_mul_f32 v[56:57], v[30:31], v[56:57]
	v_pk_mul_f32 v[54:55], v[32:33], v[54:55]
	v_cvt_pk_bf16_f32 v70, v56, v57
	v_cvt_pk_bf16_f32 v71, v54, v55
	global_store_dwordx2 v[78:79], v[70:71], off offset:1536
	v_add_u32_e32 v70, 0, v43
	v_add_u32_e32 v70, 0x18000, v70
	ds_read_b128 v[72:75], v70
	s_waitcnt lgkmcnt(0)
	v_mul_f32_e32 v71, v73, v69
	v_fmac_f32_e32 v71, v72, v68
	v_mul_f32_e32 v72, v75, v67
	v_fmac_f32_e32 v72, v74, v66
	v_add_f32_e32 v71, v71, v72
	ds_read_b128 v[72:75], v70 offset:1024
	v_add_f32_e32 v71, 0, v71
	s_waitcnt lgkmcnt(0)
	v_mul_f32_e32 v73, v73, v63
	v_fmac_f32_e32 v73, v72, v62
	v_mul_f32_e32 v72, v75, v59
	v_fmac_f32_e32 v72, v74, v58
	v_add_f32_e32 v72, v73, v72
	v_add_f32_e32 v71, v72, v71
	ds_read_b128 v[72:75], v70 offset:2048
	s_waitcnt lgkmcnt(0)
	v_mul_f32_e32 v73, v73, v65
	v_fmac_f32_e32 v73, v72, v64
	v_mul_f32_e32 v72, v75, v61
	v_fmac_f32_e32 v72, v74, v60
	v_add_f32_e32 v72, v73, v72
	v_add_f32_e32 v71, v72, v71
	ds_read_b128 v[72:75], v70 offset:3072
	s_waitcnt lgkmcnt(0)
	v_mul_f32_e32 v73, v73, v57
	v_fmac_f32_e32 v73, v72, v56
	v_mul_f32_e32 v72, v75, v55
	v_fmac_f32_e32 v72, v74, v54
	v_add_f32_e32 v72, v73, v72
	v_add_f32_e32 v71, v72, v71
	ds_read_b128 v[72:75], v70 offset:4096
	s_waitcnt lgkmcnt(0)
	v_mul_f32_e32 v73, v73, v69
	v_fmac_f32_e32 v73, v72, v68
	v_mul_f32_e32 v72, v75, v67
	v_fmac_f32_e32 v72, v74, v66
	v_add_f32_e32 v72, v73, v72
	v_add_f32_e32 v76, 0, v72
	ds_read_b128 v[72:75], v70 offset:5120
	s_waitcnt lgkmcnt(0)
	v_mul_f32_e32 v73, v73, v63
	v_fmac_f32_e32 v73, v72, v62
	v_mul_f32_e32 v72, v75, v59
	v_fmac_f32_e32 v72, v74, v58
	v_add_f32_e32 v72, v73, v72
	v_add_f32_e32 v76, v72, v76
	ds_read_b128 v[72:75], v70 offset:6144
	s_waitcnt lgkmcnt(0)
	v_mul_f32_e32 v73, v73, v65
	v_fmac_f32_e32 v73, v72, v64
	v_mul_f32_e32 v72, v75, v61
	v_fmac_f32_e32 v72, v74, v60
	v_add_f32_e32 v72, v73, v72
	v_add_f32_e32 v76, v72, v76
	ds_read_b128 v[72:75], v70 offset:7168
	s_waitcnt lgkmcnt(0)
	v_mul_f32_e32 v73, v73, v57
	v_fmac_f32_e32 v73, v72, v56
	v_mul_f32_e32 v72, v75, v55
	v_fmac_f32_e32 v72, v74, v54
	v_add_f32_e32 v72, v73, v72
	v_add_f32_e32 v72, v72, v76
	ds_read_b128 v[74:77], v70 offset:8192
	s_waitcnt lgkmcnt(0)
	v_mul_f32_e32 v73, v75, v69
	v_fmac_f32_e32 v73, v74, v68
	v_mul_f32_e32 v74, v77, v67
	v_fmac_f32_e32 v74, v76, v66
	v_add_f32_e32 v73, v73, v74
	ds_read_b128 v[74:77], v70 offset:9216
	v_add_f32_e32 v73, 0, v73
	s_waitcnt lgkmcnt(0)
	v_mul_f32_e32 v75, v63, v75
	v_fmac_f32_e32 v75, v62, v74
	v_mul_f32_e32 v74, v59, v77
	v_fmac_f32_e32 v74, v58, v76
	v_add_f32_e32 v74, v75, v74
	v_add_f32_e32 v73, v74, v73
	ds_read_b128 v[74:77], v70 offset:10240
	s_waitcnt lgkmcnt(0)
	v_mul_f32_e32 v75, v65, v75
	v_fmac_f32_e32 v75, v64, v74
	v_mul_f32_e32 v74, v61, v77
	v_fmac_f32_e32 v74, v60, v76
	v_add_f32_e32 v74, v75, v74
	v_add_f32_e32 v73, v74, v73
	ds_read_b128 v[74:77], v70 offset:11264
	s_waitcnt lgkmcnt(0)
	v_mul_f32_e32 v75, v57, v75
	v_fmac_f32_e32 v75, v56, v74
	v_mul_f32_e32 v74, v55, v77
	v_fmac_f32_e32 v74, v54, v76
	v_add_f32_e32 v74, v75, v74
	v_add_f32_e32 v73, v74, v73
	ds_read_b128 v[74:77], v70 offset:12288
	s_waitcnt lgkmcnt(0)
	v_mul_f32_e32 v75, v69, v75
	v_fmac_f32_e32 v75, v68, v74
	v_mul_f32_e32 v74, v67, v77
	v_fmac_f32_e32 v74, v66, v76
	v_add_f32_e32 v74, v75, v74
	v_add_f32_e32 v78, 0, v74
	ds_read_b128 v[74:77], v70 offset:13312
	s_waitcnt lgkmcnt(0)
; #define LAS __attribute__((address_space(3)))
; __device__ __forceinline__ void ew_phase(const Frame& F, const bf16_t* f, const float* gpost, float alpha, const float* hin, float* hout, const float* gpre, bf16_t* xn, ...
;     ...
;                 for (int k = 0; k < 8; ++k)
; #pragma unroll
;                     for (int j = 0; j < 4; ++j) { const f32x4 w4 = *(const LAS f32x4*)(WF + k * DM + 256 * j + 4 * F.lane);
;                         a8[k] += (hv[j].x * w4.x + hv[j].y * w4.y) + (hv[j].z * w4.z + hv[j].w * w4.w); }
;                 const bool b5 = (F.lane & 32) != 0, b4 = (F.lane & 16) != 0, b3 = (F.lane & 8) != 0;
;                 float r4[4], r2v[2], r1;
; #pragma unroll
;                 for (int k = 0; k < 4; ++k) { const float keep = b5 ? a8[k + 4] : a8[k], give = b5 ? a8[k] : a8[k + 4]; r4[k] = keep + __shfl_xor(give, 32); }
; #pragma unroll
;                 for (int k = 0; k < 2; ++k) { const float keep = b4 ? r4[k + 2] : r4[k], give = b4 ? r4[k] : r4[k + 2]; r2v[k] = keep + __shfl_xor(give, 16); }
;                 { const float keep = b3 ? r2v[1] : r2v[0], give = b3 ? r2v[0] : r2v[1]; r1 = keep + __shfl_xor(give, 8); }
;                 r1 += __shfl_xor(r1, 4); r1 += __shfl_xor(r1, 2); r1 += __shfl_xor(r1, 1);
;                 if ((F.lane & 7) == 0) { const int k = (b5 ? 4 : 0) + (b4 ? 2 : 0) + (b3 ? 1 : 0); const float x = r1 + bfl[k];
	v_mul_f32_e32 v75, v63, v75
	v_fmac_f32_e32 v75, v62, v74
	v_mul_f32_e32 v74, v59, v77
	v_fmac_f32_e32 v74, v58, v76
	v_add_f32_e32 v74, v75, v74
	v_add_f32_e32 v78, v78, v74
	ds_read_b128 v[74:77], v70 offset:14336
	s_waitcnt lgkmcnt(0)
	v_mul_f32_e32 v75, v65, v75
	v_fmac_f32_e32 v75, v64, v74
	v_mul_f32_e32 v74, v61, v77
	v_fmac_f32_e32 v74, v60, v76
	v_add_f32_e32 v74, v75, v74
	v_add_f32_e32 v78, v78, v74
	ds_read_b128 v[74:77], v70 offset:15360
	s_waitcnt lgkmcnt(0)
	v_mul_f32_e32 v75, v57, v75
	v_fmac_f32_e32 v75, v56, v74
	v_mul_f32_e32 v74, v55, v77
	v_fmac_f32_e32 v74, v54, v76
	v_add_f32_e32 v74, v75, v74
	v_add_f32_e32 v74, v78, v74
	ds_read_b128 v[76:79], v70 offset:16384
	s_waitcnt lgkmcnt(0)
	v_mul_f32_e32 v75, v69, v77
	v_fmac_f32_e32 v75, v68, v76
	v_mul_f32_e32 v76, v67, v79
	v_fmac_f32_e32 v76, v66, v78
	v_add_f32_e32 v75, v75, v76
	ds_read_b128 v[76:79], v70 offset:17408
	v_add_f32_e32 v75, 0, v75
	s_waitcnt lgkmcnt(0)
	v_mul_f32_e32 v77, v63, v77
	v_fmac_f32_e32 v77, v62, v76
	v_mul_f32_e32 v76, v59, v79
	v_fmac_f32_e32 v76, v58, v78
	v_add_f32_e32 v76, v77, v76
	v_add_f32_e32 v75, v75, v76
	ds_read_b128 v[76:79], v70 offset:18432
	s_waitcnt lgkmcnt(0)
	v_mul_f32_e32 v77, v65, v77
	v_fmac_f32_e32 v77, v64, v76
	v_mul_f32_e32 v76, v61, v79
	v_fmac_f32_e32 v76, v60, v78
	v_add_f32_e32 v76, v77, v76
	v_add_f32_e32 v75, v75, v76
	ds_read_b128 v[76:79], v70 offset:19456
	s_waitcnt lgkmcnt(0)
	v_mul_f32_e32 v77, v57, v77
	v_fmac_f32_e32 v77, v56, v76
	v_mul_f32_e32 v76, v55, v79
	v_fmac_f32_e32 v76, v54, v78
	v_add_f32_e32 v76, v77, v76
	v_add_f32_e32 v75, v75, v76
	ds_read_b128 v[76:79], v70 offset:20480
	s_waitcnt lgkmcnt(0)
	v_mul_f32_e32 v77, v69, v77
	v_fmac_f32_e32 v77, v68, v76
	v_mul_f32_e32 v76, v67, v79
	v_fmac_f32_e32 v76, v66, v78
	v_add_f32_e32 v76, v77, v76
	v_add_f32_e32 v80, 0, v76
	ds_read_b128 v[76:79], v70 offset:21504
	s_waitcnt lgkmcnt(0)
	v_mul_f32_e32 v77, v63, v77
	v_fmac_f32_e32 v77, v62, v76
	v_mul_f32_e32 v76, v59, v79
	v_fmac_f32_e32 v76, v58, v78
	v_add_f32_e32 v76, v77, v76
	v_add_f32_e32 v80, v80, v76
	ds_read_b128 v[76:79], v70 offset:22528
	s_waitcnt lgkmcnt(0)
	v_mul_f32_e32 v77, v65, v77
	v_fmac_f32_e32 v77, v64, v76
	v_mul_f32_e32 v76, v61, v79
	v_fmac_f32_e32 v76, v60, v78
	v_add_f32_e32 v76, v77, v76
	v_add_f32_e32 v80, v80, v76
	ds_read_b128 v[76:79], v70 offset:23552
	s_waitcnt lgkmcnt(0)
	v_mul_f32_e32 v77, v57, v77
	v_fmac_f32_e32 v77, v56, v76
	v_mul_f32_e32 v76, v55, v79
	v_fmac_f32_e32 v76, v54, v78
	v_add_f32_e32 v76, v77, v76
	v_add_f32_e32 v80, v80, v76
	ds_read_b128 v[76:79], v70 offset:24576
	s_waitcnt lgkmcnt(0)
	v_mul_f32_e32 v77, v69, v77
	v_fmac_f32_e32 v77, v68, v76
	v_mul_f32_e32 v76, v67, v79
	v_fmac_f32_e32 v76, v66, v78
	v_add_f32_e32 v76, v77, v76
	v_add_f32_e32 v81, 0, v76
	ds_read_b128 v[76:79], v70 offset:25600
	s_waitcnt lgkmcnt(0)
	v_mul_f32_e32 v77, v63, v77
	v_fmac_f32_e32 v77, v62, v76
	v_mul_f32_e32 v76, v59, v79
	v_fmac_f32_e32 v76, v58, v78
	v_add_f32_e32 v76, v77, v76
	v_add_f32_e32 v81, v81, v76
	ds_read_b128 v[76:79], v70 offset:26624
	s_waitcnt lgkmcnt(0)
	v_mul_f32_e32 v77, v65, v77
	v_fmac_f32_e32 v77, v64, v76
	v_mul_f32_e32 v76, v61, v79
	v_fmac_f32_e32 v76, v60, v78
	v_add_f32_e32 v76, v77, v76
	v_add_f32_e32 v81, v81, v76
	ds_read_b128 v[76:79], v70 offset:27648
	s_waitcnt lgkmcnt(0)
	v_mul_f32_e32 v77, v57, v77
	v_fmac_f32_e32 v77, v56, v76
	v_mul_f32_e32 v76, v55, v79
	v_fmac_f32_e32 v76, v54, v78
	v_add_f32_e32 v76, v77, v76
	v_add_f32_e32 v81, v81, v76
	ds_read_b128 v[76:79], v70 offset:28672
	s_waitcnt lgkmcnt(0)
	v_mul_f32_e32 v69, v69, v77
	v_mul_f32_e32 v67, v67, v79
	v_fmac_f32_e32 v69, v68, v76
	v_fmac_f32_e32 v67, v66, v78
	v_add_f32_e32 v66, v69, v67
	v_add_f32_e32 v76, 0, v66
	ds_read_b128 v[66:69], v70 offset:29696
	s_waitcnt lgkmcnt(0)
	v_mul_f32_e32 v63, v63, v67
	v_mul_f32_e32 v59, v59, v69
	v_fmac_f32_e32 v63, v62, v66
	v_fmac_f32_e32 v59, v58, v68
	ds_read_b128 v[66:69], v70 offset:30720
	v_add_f32_e32 v58, v63, v59
	v_add_f32_e32 v58, v76, v58
	s_waitcnt lgkmcnt(0)
	v_mul_f32_e32 v59, v65, v67
	v_mul_f32_e32 v61, v61, v69
	v_fmac_f32_e32 v59, v64, v66
	v_fmac_f32_e32 v61, v60, v68
	v_add_f32_e32 v59, v59, v61
	v_add_f32_e32 v62, v58, v59
	ds_read_b128 v[58:61], v70 offset:31744
	s_waitcnt lgkmcnt(0)
	v_mul_f32_e32 v57, v57, v59
	v_mul_f32_e32 v55, v55, v61
	v_fmac_f32_e32 v57, v56, v58
	v_fmac_f32_e32 v55, v54, v60
	v_cndmask_b32_e64 v56, v71, v75, s[36:37]
	v_add_f32_e32 v54, v57, v55
	ds_bpermute_b32 v56, v100, v56
	v_cndmask_b32_e64 v57, v72, v80, s[36:37]
	ds_bpermute_b32 v57, v100, v57
	v_cndmask_b32_e64 v58, v73, v81, s[36:37]
	ds_bpermute_b32 v58, v100, v58
	v_cndmask_b32_e64 v55, v75, v71, s[36:37]
	s_waitcnt lgkmcnt(2)
	v_add_f32_e32 v55, v55, v56
	v_cndmask_b32_e64 v56, v80, v72, s[36:37]
	v_add_f32_e32 v54, v62, v54
	s_waitcnt lgkmcnt(1)
	v_add_f32_e32 v56, v56, v57
	v_cndmask_b32_e64 v57, v81, v73, s[36:37]
	s_waitcnt lgkmcnt(0)
	v_add_f32_e32 v57, v57, v58
	v_cndmask_b32_e64 v58, v54, v74, s[36:37]
	v_cndmask_b32_e64 v54, v74, v54, s[36:37]
	ds_bpermute_b32 v54, v100, v54
	s_waitcnt lgkmcnt(0)
	v_add_f32_e32 v54, v58, v54
	v_cndmask_b32_e64 v58, v57, v55, s[38:39]
	v_cndmask_b32_e64 v55, v55, v57, s[38:39]
	v_cndmask_b32_e64 v57, v54, v56, s[38:39]
	v_cndmask_b32_e64 v54, v56, v54, s[38:39]
	ds_bpermute_b32 v55, v99, v55
	ds_bpermute_b32 v54, v99, v54
	s_waitcnt lgkmcnt(1)
	v_add_f32_e32 v55, v58, v55
	s_waitcnt lgkmcnt(0)
	v_add_f32_e32 v54, v57, v54
	v_cndmask_b32_e64 v56, v54, v55, s[40:41]
	v_cndmask_b32_e64 v54, v55, v54, s[40:41]
	ds_bpermute_b32 v54, v97, v54
	s_waitcnt lgkmcnt(0)
	v_add_f32_e32 v54, v56, v54
	ds_bpermute_b32 v55, v96, v54
	s_waitcnt lgkmcnt(0)
	v_add_f32_e32 v54, v54, v55
	ds_bpermute_b32 v55, v90, v54
	s_waitcnt lgkmcnt(0)
	v_add_f32_e32 v54, v54, v55
	ds_bpermute_b32 v0, v0, v54
	s_and_saveexec_b64 s[0:1], s[42:43]
	s_cbranch_execz .LBB0_207
; __device__ __forceinline__ void ew_phase(const Frame& F, const bf16_t* f, const float* gpost, float alpha, const float* hin, float* hout, const float* gpre, bf16_t* xn, ...
;     ...
;                 if ((F.lane & 7) == 0) { const int k = (b5 ? 4 : 0) + (b4 ? 2 : 0) + (b3 ? 1 : 0); const float x = r1 + bfl[k];
;                     const float ls = fminf(x, 0.f) - log1pf(expf(-fabsf(x))); logf[(size_t)k * T + m] = ls * LOG2E; logf[(size_t)T * 8 + (size_t)k * T + m] = 0.f; }
	global_load_dword v55, v[48:49], off
	s_waitcnt lgkmcnt(0)
	v_add_f32_e32 v0, v54, v0
	s_lshl_b64 s[2:3], s[10:11], 2
	s_waitcnt vmcnt(0)
	v_add_f32_e32 v0, v0, v55
	v_mul_f32_e64 v54, |v0|, s27
	v_fma_f32 v55, |v0|, s27, -v54
	v_rndne_f32_e32 v56, v54
	v_fma_f32 v55, |v0|, s35, v55
	v_sub_f32_e32 v54, v54, v56
	v_add_f32_e32 v54, v54, v55
	v_cvt_i32_f32_e32 v58, v56
	v_exp_f32_e32 v59, v54
	v_lshl_add_u64 v[54:55], v[50:51], 0, s[2:3]
	v_lshl_add_u64 v[56:57], v[52:53], 0, s[2:3]
	s_mov_b32 s2, 0x42ce8ed0
	v_ldexp_f32 v58, v59, v58
	v_cmp_ngt_f32_e64 vcc, |v0|, s2
	s_mov_b32 s2, 0xc2b17218
	v_min_f32_e32 v60, 0, v0
	v_cndmask_b32_e32 v58, 0, v58, vcc
	v_cmp_nlt_f32_e64 vcc, |v0|, s2
	s_mov_b32 s2, 0x3f2aaaab
	s_nop 0
	v_cndmask_b32_e32 v0, v107, v58, vcc
	v_add_f32_e32 v61, 1.0, v0
	v_add_f32_e32 v62, -1.0, v61
	v_frexp_mant_f32_e32 v63, v61
	v_cvt_f64_f32_e32 v[58:59], v61
	v_sub_f32_e32 v64, v62, v61
	v_frexp_exp_i32_f64_e32 v58, v[58:59]
	v_cmp_gt_f32_e32 vcc, s2, v63
	v_sub_f32_e32 v62, v0, v62
	v_add_f32_e32 v59, 1.0, v64
	v_subbrev_co_u32_e32 v58, vcc, 0, v58, vcc
	v_add_f32_e32 v59, v62, v59
	v_sub_u32_e32 v62, 0, v58
	v_cvt_f32_i32_e32 v58, v58
	v_ldexp_f32 v61, v61, v62
	v_ldexp_f32 v59, v59, v62
	v_add_f32_e32 v62, -1.0, v61
	v_add_f32_e32 v63, 1.0, v61
	v_add_f32_e32 v64, 1.0, v62
	v_add_f32_e32 v65, -1.0, v63
	v_sub_f32_e32 v64, v61, v64
	v_sub_f32_e32 v61, v61, v65
	v_mul_f32_e32 v65, 0x3f317218, v58
	v_add_f32_e32 v64, v59, v64
	v_add_f32_e32 v59, v59, v61
	s_mov_b32 s2, 0x3f317218
	v_fma_f32 v61, v58, s2, -v65
	v_add_f32_e32 v66, v62, v64
	v_add_f32_e32 v67, v63, v59
	v_fmac_f32_e32 v61, 0xb102e308, v58
	v_sub_f32_e32 v58, v62, v66
	v_sub_f32_e32 v62, v63, v67
	v_rcp_f32_e32 v63, v67
	v_add_f32_e32 v68, v65, v61
	v_add_f32_e32 v59, v59, v62
	v_sub_f32_e32 v62, v68, v65
	v_sub_f32_e32 v61, v61, v62
	v_mul_f32_e32 v62, v66, v63
	v_add_f32_e32 v58, v64, v58
	v_mul_f32_e32 v64, v67, v62
	v_fma_f32 v65, v62, v67, -v64
	v_fmac_f32_e32 v65, v62, v59
	v_add_f32_e32 v69, v64, v65
	v_sub_f32_e32 v70, v66, v69
	v_sub_f32_e32 v64, v69, v64
	v_sub_f32_e32 v66, v66, v70
	v_sub_f32_e32 v64, v64, v65
	v_sub_f32_e32 v65, v66, v69
	v_add_f32_e32 v58, v58, v65
	v_add_f32_e32 v58, v64, v58
	v_add_f32_e32 v64, v70, v58
	v_mul_f32_e32 v65, v63, v64
	v_sub_f32_e32 v66, v70, v64
	v_mul_f32_e32 v69, v67, v65
	v_add_f32_e32 v58, v58, v66
	v_add_f32_e32 v66, v62, v65
	v_fma_f32 v67, v65, v67, -v69
	v_sub_f32_e32 v62, v66, v62
	v_fmac_f32_e32 v67, v65, v59
	v_sub_f32_e32 v59, v65, v62
	v_add_f32_e32 v62, v69, v67
	v_sub_f32_e32 v65, v62, v69
	v_sub_f32_e32 v69, v64, v62
	v_sub_f32_e32 v64, v64, v69
	v_sub_f32_e32 v62, v64, v62
	v_sub_f32_e32 v65, v65, v67
	v_add_f32_e32 v58, v58, v62
	v_add_f32_e32 v58, v65, v58
	v_add_f32_e32 v58, v69, v58
	v_mul_f32_e32 v58, v63, v58
	v_add_f32_e32 v58, v59, v58
	v_add_f32_e32 v59, v66, v58
	v_mul_f32_e32 v62, v59, v59
	v_fmamk_f32 v65, v62, 0x3e9b6dac, v235
	v_sub_f32_e32 v63, v59, v66
	v_ldexp_f32 v64, v59, 1
	v_mul_f32_e32 v59, v59, v62
	v_fmaak_f32 v62, v62, v65, 0x3f2aaada
	v_mul_f32_e32 v59, v59, v62
	v_add_f32_e32 v62, v64, v59
	v_sub_f32_e32 v58, v58, v63
	v_sub_f32_e32 v63, v62, v64
	v_ldexp_f32 v58, v58, 1
	v_sub_f32_e32 v59, v59, v63
	v_add_f32_e32 v58, v58, v59
	v_add_f32_e32 v59, v62, v58
	v_sub_f32_e32 v62, v59, v62
	v_add_f32_e32 v63, v68, v59
	v_sub_f32_e32 v58, v58, v62
	v_sub_f32_e32 v62, v63, v68
	v_sub_f32_e32 v64, v63, v62
	v_sub_f32_e32 v59, v59, v62
	v_add_f32_e32 v62, v61, v58
	v_sub_f32_e32 v64, v68, v64
	v_sub_f32_e32 v65, v62, v61
	v_add_f32_e32 v59, v59, v64
	v_sub_f32_e32 v64, v62, v65
	v_sub_f32_e32 v58, v58, v65
	v_sub_f32_e32 v61, v61, v64
	v_add_f32_e32 v59, v62, v59
	v_add_f32_e32 v58, v58, v61
	v_add_f32_e32 v61, v63, v59
	v_sub_f32_e32 v62, v61, v63
	v_sub_f32_e32 v59, v59, v62
	v_add_f32_e32 v58, v58, v59
	s_mov_b32 s2, 0x7f800000
	v_add_f32_e32 v58, v61, v58
	v_cmp_neq_f32_e32 vcc, s2, v0
	s_mov_b32 s2, 0x33800000
	s_nop 0
	v_cndmask_b32_e32 v58, v107, v58, vcc
	v_cmp_lt_f32_e64 vcc, |v0|, s2
	s_nop 1
	v_cndmask_b32_e32 v0, v58, v0, vcc
	v_sub_f32_e32 v0, v60, v0
	v_mul_f32_e32 v0, 0x3fb8aa3b, v0
	global_store_dword v[54:55], v0, off
	global_store_dword v[56:57], v1, off
	s_branch .LBB0_207

; __device__ __forceinline__ float bf_lo(unsigned w) { return __uint_as_float(w << 16); }
; __device__ __forceinline__ float bf_hi(unsigned w) { return __uint_as_float(w & 0xffff0000u); }
; __device__ __forceinline__ void ew_phase(const Frame& F, const bf16_t* f, const float* gpost, float alpha, const float* hin, float* hout, const float* gpre, bf16_t* xn, ...
;     ...
;     for (int it_ = 0; it_ < it_n; ++it_) {
;         const int m = prow0 >= 0 ? prow0 + F.wave * 8 + it_ : F.gw + it_ * F.NGW; if (m >= T) break;
;         const u32x2* fr = (const u32x2*)(f + (size_t)m * DM) + F.lane; const f32x4* hr = (const f32x4*)(hin + (size_t)m * DM) + F.lane;
;         f32x4 fv[4], hv[4]; float s = 0.f;
; #pragma unroll
;         for (int j = 0; j < 4; ++j) { const u32x2 w = fr[64 * j]; hv[j] = in24 ? load24(h24 + (size_t)m * (DM * 3), F.lane + 64 * j) : hr[64 * j]; fv[j] = (f32x4){bf_lo(w.x), bf_hi(w.x), bf_lo(w.y), bf_hi(w.y)};
;             s += (fv[j].x * fv[j].x + fv[j].y * fv[j].y) + (fv[j].z * fv[j].z + fv[j].w * fv[j].w); }
;         const float rstd = alpha / sqrtf(wave_sum(s) * (1.f / DM) + RMS_EPS);
.LBB0_812:
	v_readlane_b32 s0, v252, 11
	s_add_i32 s8, s2, s3
	v_readlane_b32 s1, v252, 12
	s_and_b64 s[0:1], s[0:1], exec
	s_cselect_b32 s8, s8, s12
	s_cmpk_gt_i32 s8, 0x3fff
	s_mov_b64 s[0:1], -1
	s_cbranch_scc1 .LBB0_811
	s_ashr_i32 s9, s8, 31
	s_lshl_b64 s[0:1], s[8:9], 11
	v_lshl_add_u64 v[78:79], v[36:37], 0, s[0:1]
	s_mul_i32 s0, s8, 0xc00
	s_mul_hi_i32 s1, s8, 0xc00
	s_add_u32 s0, s25, s0
	s_addc_u32 s1, s27, s1
	v_lshl_add_u64 v[48:49], s[0:1], 0, v[40:41]
	v_lshl_add_u64 v[162:163], s[0:1], 0, v[42:43]
	v_lshl_add_u64 v[164:165], s[0:1], 0, v[44:45]
	v_lshl_add_u64 v[166:167], s[0:1], 0, v[46:47]
	global_load_dwordx2 v[56:57], v[78:79], off
	global_load_dwordx2 v[52:53], v[48:49], off
	global_load_dwordx2 v[54:55], v[48:49], off offset:4
	global_load_dwordx2 v[64:65], v[78:79], off offset:512
	global_load_dwordx2 v[62:63], v[162:163], off
	global_load_dwordx2 v[66:67], v[162:163], off offset:4
	global_load_dwordx2 v[76:77], v[78:79], off offset:1024
	global_load_dwordx2 v[72:73], v[164:165], off
	global_load_dwordx2 v[74:75], v[164:165], off offset:4
	global_load_dwordx2 v[84:85], v[78:79], off offset:1536
	global_load_dwordx2 v[82:83], v[166:167], off
	global_load_dwordx2 v[86:87], v[166:167], off offset:4
	s_mov_b32 s14, 0xff00
	s_waitcnt vmcnt(10)
	v_lshrrev_b32_e32 v53, 8, v53
	s_waitcnt vmcnt(9)
	v_lshlrev_b32_e32 v51, 24, v55
	v_lshlrev_b32_e32 v54, 16, v54
	v_and_b32_e32 v53, 0xffff00, v53
	v_and_b32_sdwa v58, v52, s14 dst_sel:DWORD dst_unused:UNUSED_PAD src0_sel:WORD_1 src1_sel:DWORD
	v_lshlrev_b32_e32 v50, 8, v52
	v_or_b32_e32 v52, v51, v53
	v_or_b32_e32 v51, v54, v58
	v_and_b32_e32 v53, 0xffffff00, v55
	v_lshlrev_b32_e32 v54, 16, v56
	v_and_b32_e32 v55, 0xffff0000, v56
	v_lshlrev_b32_e32 v56, 16, v57
	v_and_b32_e32 v57, 0xffff0000, v57
	v_mul_f32_e32 v58, v57, v57
	v_pk_fma_f32 v[90:91], v[56:57], v[56:57], v[58:59] op_sel_hi:[1,1,0]
	v_lshl_add_u64 v[58:59], s[0:1], 0, v[42:43]
	v_mov_b32_e32 v98, v90
	s_waitcnt vmcnt(7)
	v_lshrrev_b32_e32 v63, 8, v63
	s_waitcnt vmcnt(6)
	v_lshlrev_b32_e32 v61, 24, v67
	v_lshlrev_b32_e32 v66, 16, v66
	v_and_b32_e32 v63, 0xffff00, v63
	v_and_b32_sdwa v68, v62, s14 dst_sel:DWORD dst_unused:UNUSED_PAD src0_sel:WORD_1 src1_sel:DWORD
	v_lshlrev_b32_e32 v60, 8, v62
	v_or_b32_e32 v62, v61, v63
	v_or_b32_e32 v61, v66, v68
	v_and_b32_e32 v63, 0xffffff00, v67
	v_lshlrev_b32_e32 v67, 16, v65
	v_lshlrev_b32_e32 v66, 16, v64
	v_and_b32_e32 v65, 0xffff0000, v65
	v_and_b32_e32 v64, 0xffff0000, v64
	v_pk_mul_f32 v[68:69], v[64:65], v[64:65]
	s_nop 0
	v_pk_fma_f32 v[94:95], v[66:67], v[66:67], v[68:69]
	v_lshl_add_u64 v[68:69], s[0:1], 0, v[44:45]
	v_lshl_add_u64 v[78:79], s[0:1], 0, v[46:47]
	v_pk_add_f32 v[94:95], v[94:95], v[94:95] op_sel:[0,1] op_sel_hi:[1,0]
	s_waitcnt vmcnt(4)
	v_lshrrev_b32_e32 v73, 8, v73
	s_waitcnt vmcnt(3)
	v_lshlrev_b32_e32 v71, 24, v75
	v_lshlrev_b32_e32 v74, 16, v74
	s_waitcnt vmcnt(1)
	v_lshrrev_b32_e32 v83, 8, v83
	v_and_b32_e32 v73, 0xffff00, v73
	v_and_b32_sdwa v80, v72, s14 dst_sel:DWORD dst_unused:UNUSED_PAD src0_sel:WORD_1 src1_sel:DWORD
	s_waitcnt vmcnt(0)
	v_lshlrev_b32_e32 v81, 24, v87
	v_lshlrev_b32_e32 v86, 16, v86
	v_and_b32_e32 v83, 0xffff00, v83
	v_and_b32_sdwa v88, v82, s14 dst_sel:DWORD dst_unused:UNUSED_PAD src0_sel:WORD_1 src1_sel:DWORD
	v_lshlrev_b32_e32 v70, 8, v72
	v_or_b32_e32 v72, v71, v73
	v_or_b32_e32 v71, v74, v80
	v_lshlrev_b32_e32 v80, 8, v82
	v_or_b32_e32 v82, v81, v83
	v_or_b32_e32 v81, v86, v88
	v_and_b32_e32 v83, 0xffffff00, v87
	v_and_b32_e32 v87, 0xffff0000, v84
	v_mul_f32_e32 v86, v55, v55
	v_lshlrev_b32_e32 v89, 16, v84
	v_pk_fma_f32 v[96:97], v[54:55], v[54:55], v[86:87] op_sel_hi:[1,1,0]
	v_mov_b32_e32 v99, v89
	v_mov_b32_e32 v88, v96
	v_and_b32_e32 v73, 0xffffff00, v75
	v_and_b32_e32 v75, 0xffff0000, v76
	v_mul_f32_e32 v93, v87, v87
	v_pk_add_f32 v[90:91], v[96:97], v[90:91]
	v_pk_mul_f32 v[96:97], v[88:89], v[98:99]
	v_lshlrev_b32_e32 v74, 16, v76
	v_lshlrev_b32_e32 v76, 16, v77
	v_and_b32_e32 v77, 0xffff0000, v77
	v_mov_b32_e32 v91, v97
	v_mov_b32_e32 v95, v93
	v_mul_f32_e32 v86, v75, v75
	v_lshlrev_b32_e32 v84, 16, v85
	v_and_b32_e32 v85, 0xffff0000, v85
	v_pk_add_f32 v[90:91], v[90:91], v[94:95]
	v_pk_fma_f32 v[94:95], v[74:75], v[74:75], v[86:87] op_sel_hi:[1,1,0]
	v_mul_f32_e32 v86, v77, v77
	v_mul_f32_e32 v100, v84, v84
	v_mul_f32_e32 v101, v85, v85
	v_pk_fma_f32 v[96:97], v[76:77], v[76:77], v[86:87] op_sel_hi:[1,1,0]
	v_mov_b32_e32 v95, v100
	v_mov_b32_e32 v97, v101
	v_pk_add_f32 v[94:95], v[94:95], v[96:97]
	v_and_b32_e32 v88, 64, v230
	v_pk_add_f32 v[90:91], v[90:91], v[94:95]
	v_add_u32_e32 v95, 64, v88
	v_xor_b32_e32 v88, 1, v230
	v_cmp_lt_i32_e32 vcc, v88, v95
	v_add_f32_e32 v86, v90, v91
	s_mov_b32 s14, 0xf800000
	v_cndmask_b32_e32 v88, v230, v88, vcc
	v_lshlrev_b32_e32 v88, 2, v88
	ds_bpermute_b32 v90, v88, v86
	s_waitcnt lgkmcnt(0)
	v_add_f32_e32 v86, v86, v90
	v_xor_b32_e32 v90, 2, v230
	v_cmp_lt_i32_e32 vcc, v90, v95
	s_nop 1
	v_cndmask_b32_e32 v90, v230, v90, vcc
	v_lshlrev_b32_e32 v90, 2, v90
	ds_bpermute_b32 v91, v90, v86
	s_waitcnt lgkmcnt(0)
	v_add_f32_e32 v86, v86, v91
	v_xor_b32_e32 v91, 4, v230
	v_cmp_lt_i32_e32 vcc, v91, v95
	s_nop 1
	v_cndmask_b32_e32 v91, v230, v91, vcc
	v_lshlrev_b32_e32 v91, 2, v91
	ds_bpermute_b32 v93, v91, v86
	s_waitcnt lgkmcnt(0)
	v_add_f32_e32 v86, v86, v93
	v_xor_b32_e32 v93, 8, v230
	v_cmp_lt_i32_e32 vcc, v93, v95
	s_nop 1
	v_cndmask_b32_e32 v93, v230, v93, vcc
	v_lshlrev_b32_e32 v93, 2, v93
	ds_bpermute_b32 v94, v93, v86
	s_waitcnt lgkmcnt(0)
	v_add_f32_e32 v86, v86, v94
	v_xor_b32_e32 v94, 16, v230
	v_cmp_lt_i32_e32 vcc, v94, v95
	s_nop 1
	v_cndmask_b32_e32 v94, v230, v94, vcc
	v_lshlrev_b32_e32 v94, 2, v94
	ds_bpermute_b32 v96, v94, v86
	s_waitcnt lgkmcnt(0)
; __device__ __forceinline__ void ew_phase(const Frame& F, const bf16_t* f, const float* gpost, float alpha, const float* hin, float* hout, const float* gpre, bf16_t* xn, ...
;     ...
;         const float rstd = alpha / sqrtf(wave_sum(s) * (1.f / DM) + RMS_EPS);
;         float s2 = 0.f; f32x4* ho = (f32x4*)(hout + (size_t)m * DM) + F.lane;
; #pragma unroll
;         for (int j = 0; j < 4; ++j) { hv[j] = hv[j] + fv[j] * rstd * gp[j]; if (out24) store24(h24 + (size_t)m * (DM * 3), F.lane + 64 * j, hv[j]); else ho[64 * j] = hv[j]; s2 += (hv[j].x * hv[j].x + hv[j].y * hv[j].y) + (hv[j].z * hv[j].z + hv[j].w * hv[j].w); }
;         if (gpre) {
	v_add_f32_e32 v86, v86, v96
	v_xor_b32_e32 v96, 32, v230
	v_cmp_lt_i32_e32 vcc, v96, v95
	s_nop 1
	v_cndmask_b32_e32 v95, v230, v96, vcc
	v_lshlrev_b32_e32 v95, 2, v95
	ds_bpermute_b32 v96, v95, v86
	s_waitcnt lgkmcnt(0)
	v_add_f32_e32 v86, v86, v96
	v_fmamk_f32 v86, v86, 0x3a800000, v225
	v_cmp_gt_f32_e32 vcc, s14, v86
	v_mul_f32_e32 v96, 0x4f800000, v86
	s_nop 0
	v_cndmask_b32_e32 v86, v86, v96, vcc
	v_sqrt_f32_e32 v96, v86
	s_nop 0
	v_add_u32_e32 v97, -1, v96
	v_fma_f32 v98, -v97, v96, v86
	v_cmp_ge_f32_e64 s[0:1], 0, v98
	v_add_u32_e32 v98, 1, v96
	s_nop 0
	v_cndmask_b32_e64 v97, v96, v97, s[0:1]
	v_fma_f32 v96, -v98, v96, v86
	v_cmp_lt_f32_e64 s[0:1], 0, v96
	s_nop 1
	v_cndmask_b32_e64 v96, v97, v98, s[0:1]
	v_mul_f32_e32 v97, 0x37800000, v96
	v_cndmask_b32_e32 v96, v96, v97, vcc
	v_cmp_class_f32_e32 vcc, v86, v226
	s_nop 1
	v_cndmask_b32_e32 v86, v96, v86, vcc
	v_div_scale_f32 v96, s[0:1], v86, v86, 1.0
	v_rcp_f32_e32 v97, v96
	s_mov_b32 s0, 0x7060503
	v_fma_f32 v98, -v96, v97, 1.0
	v_fmac_f32_e32 v97, v98, v97
	v_div_scale_f32 v98, vcc, 1.0, v86, 1.0
	v_mul_f32_e32 v99, v98, v97
	v_fma_f32 v100, -v96, v99, v98
	v_fmac_f32_e32 v99, v100, v97
	v_fma_f32 v96, -v96, v99, v98
	v_div_fmas_f32 v96, v96, v97, v99
	v_div_fixup_f32 v96, v96, v86, 1.0
	v_pk_mul_f32 v[54:55], v[96:97], v[54:55] op_sel_hi:[0,1]
	v_pk_mul_f32 v[56:57], v[96:97], v[56:57] op_sel_hi:[0,1]
	v_pk_fma_f32 v[52:53], v[4:5], v[56:57], v[52:53]
	v_pk_fma_f32 v[50:51], v[2:3], v[54:55], v[50:51]
	v_bfe_u32 v57, v52, 8, 1
	v_bfe_u32 v55, v51, 8, 1
	v_bfe_u32 v54, v50, 8, 1
	v_add3_u32 v55, v51, v55, s13
	v_add3_u32 v57, v52, v57, s13
	v_bfe_u32 v97, v53, 8, 1
	v_add3_u32 v54, v50, v54, s13
	v_lshrrev_b32_e32 v56, 8, v55
	v_lshrrev_b32_e32 v86, 8, v57
	v_add3_u32 v97, v53, v97, s13
	v_alignbit_b32 v54, v56, v54, 8
	v_alignbit_b32 v55, v86, v55, 16
	v_perm_b32 v56, v97, v57, s0
	global_store_dwordx3 v[48:49], v[54:56], off
	v_mov_b32_e32 v48, v66
	v_mov_b32_e32 v49, v64
	v_mov_b32_e32 v64, v67
	v_pk_mul_f32 v[54:55], v[96:97], v[48:49] op_sel_hi:[0,1]
	v_pk_mul_f32 v[48:49], v[96:97], v[64:65] op_sel_hi:[0,1]
	v_pk_fma_f32 v[48:49], v[16:17], v[48:49], v[62:63]
	v_pk_fma_f32 v[54:55], v[14:15], v[54:55], v[60:61]
	v_bfe_u32 v61, v48, 8, 1
	v_bfe_u32 v57, v55, 8, 1
	v_bfe_u32 v56, v54, 8, 1
	v_add3_u32 v57, v55, v57, s13
	v_add3_u32 v62, v48, v61, s13
	v_bfe_u32 v63, v49, 8, 1
	v_add3_u32 v56, v54, v56, s13
	v_lshrrev_b32_e32 v60, 8, v57
	v_lshrrev_b32_e32 v61, 8, v62
	v_add3_u32 v63, v49, v63, s13
	v_alignbit_b32 v60, v60, v56, 8
	v_alignbit_b32 v61, v61, v57, 16
	v_perm_b32 v62, v63, v62, s0
	global_store_dwordx3 v[58:59], v[60:62], off
	v_pk_mul_f32 v[58:59], v[96:97], v[74:75] op_sel_hi:[0,1]
	v_pk_mul_f32 v[56:57], v[96:97], v[76:77] op_sel_hi:[0,1]
	v_pk_fma_f32 v[56:57], v[20:21], v[56:57], v[72:73]
	v_pk_fma_f32 v[58:59], v[18:19], v[58:59], v[70:71]
	v_bfe_u32 v63, v56, 8, 1
	v_bfe_u32 v61, v59, 8, 1
	v_bfe_u32 v60, v58, 8, 1
	v_add3_u32 v61, v59, v61, s13
	v_add3_u32 v63, v56, v63, s13
	v_bfe_u32 v65, v57, 8, 1
	v_add3_u32 v60, v58, v60, s13
	v_lshrrev_b32_e32 v62, 8, v61
	v_lshrrev_b32_e32 v64, 8, v63
	v_add3_u32 v65, v57, v65, s13
	v_alignbit_b32 v60, v62, v60, 8
	v_alignbit_b32 v61, v64, v61, 16
	v_perm_b32 v62, v65, v63, s0
	v_mov_b32_e32 v86, v89
	global_store_dwordx3 v[68:69], v[60:62], off
	s_and_b64 vcc, exec, s[40:41]
	s_nop 0
	v_pk_mul_f32 v[62:63], v[86:87], v[96:97] op_sel_hi:[1,0]
	v_pk_mul_f32 v[60:61], v[84:85], v[96:97] op_sel_hi:[1,0]
	v_pk_fma_f32 v[62:63], v[30:31], v[62:63], v[80:81]
	v_pk_fma_f32 v[60:61], v[32:33], v[60:61], v[82:83]
	v_bfe_u32 v65, v63, 8, 1
	v_bfe_u32 v67, v60, 8, 1
	v_bfe_u32 v64, v62, 8, 1
	v_add3_u32 v65, v63, v65, s13
	v_add3_u32 v67, v60, v67, s13
	v_bfe_u32 v69, v61, 8, 1
	v_add3_u32 v64, v62, v64, s13
	v_lshrrev_b32_e32 v66, 8, v65
	v_lshrrev_b32_e32 v68, 8, v67
	v_add3_u32 v69, v61, v69, s13
	v_alignbit_b32 v64, v66, v64, 8
	v_alignbit_b32 v65, v68, v65, 16
	v_perm_b32 v66, v69, v67, s0
	global_store_dwordx3 v[78:79], v[64:66], off
	s_cbranch_vccnz .LBB0_810
; __device__ __forceinline__ unsigned cvt_pk_bf16(float lo, float hi) { f32x2 v = {lo, hi}; bf16x2_t b = __builtin_convertvector(v, bf16x2_t); return __builtin_bit_cast(unsigned, b); }
; __device__ __forceinline__ void ew_phase(const Frame& F, const bf16_t* f, const float* gpost, float alpha, const float* hin, float* hout, const float* gpre, bf16_t* xn, ...
;     ...
;         if (gpre) {
;             const float r2 = 1.0f / sqrtf(wave_sum(s2) * (1.f / DM) + RMS_EPS);
;             u32x2* o8 = (u32x2*)(xn + (size_t)m * DM) + F.lane;
; #pragma unroll
;             for (int j = 0; j < 4; ++j) { hv[j] = hv[j] * r2 * gq[j]; u32x2 w; w.x = cvt_pk_bf16(hv[j].x, hv[j].y); w.y = cvt_pk_bf16(hv[j].z, hv[j].w); o8[64 * j] = w; }
	s_nop 0
	v_pk_mul_f32 v[64:65], v[52:53], v[52:53]
	v_pk_mul_f32 v[66:67], v[50:51], v[50:51]
	v_mov_b32_e32 v69, v65
	v_mov_b32_e32 v68, v66
	v_pk_mov_b32 v[64:65], v[66:67], v[64:65] op_sel:[1,0]
	v_pk_mul_f32 v[66:67], v[48:49], v[48:49]
	v_pk_add_f32 v[64:65], v[68:69], v[64:65]
	v_pk_mul_f32 v[68:69], v[54:55], v[54:55]
	v_pk_add_f32 v[64:65], v[64:65], v[64:65] op_sel_hi:[0,1]
	v_mov_b32_e32 v70, v68
	v_mov_b32_e32 v71, v67
	v_pk_mov_b32 v[66:67], v[68:69], v[66:67] op_sel:[1,0]
	v_mul_f32_e32 v64, v58, v58
	v_pk_add_f32 v[66:67], v[70:71], v[66:67]
	v_pk_fma_f32 v[68:69], v[58:59], v[58:59], v[64:65] op_sel_hi:[1,1,0]
	v_mul_f32_e32 v64, v56, v56
	v_pk_add_f32 v[66:67], v[66:67], v[66:67] op_sel_hi:[0,1]
	v_pk_fma_f32 v[70:71], v[56:57], v[56:57], v[64:65] op_sel_hi:[1,1,0]
	v_mul_f32_e32 v68, v62, v62
	v_mul_f32_e32 v70, v63, v63
	v_mul_f32_e32 v64, v61, v61
	v_mul_f32_e32 v66, v60, v60
	v_pk_add_f32 v[68:69], v[68:69], v[70:71]
	v_pk_add_f32 v[64:65], v[64:65], v[66:67]
	s_lshl_b64 s[8:9], s[8:9], 10
	v_pk_add_f32 v[64:65], v[68:69], v[64:65]
	s_nop 0
	v_add_f32_e32 v64, v64, v65
	ds_bpermute_b32 v65, v88, v64
	s_waitcnt lgkmcnt(0)
	v_add_f32_e32 v64, v64, v65
	ds_bpermute_b32 v65, v90, v64
	s_waitcnt lgkmcnt(0)
	v_add_f32_e32 v64, v64, v65
	ds_bpermute_b32 v65, v91, v64
	s_waitcnt lgkmcnt(0)
	v_add_f32_e32 v64, v64, v65
	ds_bpermute_b32 v65, v93, v64
	s_waitcnt lgkmcnt(0)
	v_add_f32_e32 v64, v64, v65
	ds_bpermute_b32 v65, v94, v64
	s_waitcnt lgkmcnt(0)
	v_add_f32_e32 v64, v64, v65
	ds_bpermute_b32 v65, v95, v64
	s_waitcnt lgkmcnt(0)
	v_add_f32_e32 v64, v64, v65
	v_fmamk_f32 v64, v64, 0x3a800000, v225
	v_mul_f32_e32 v65, 0x4f800000, v64
	v_cmp_gt_f32_e32 vcc, s14, v64
	s_nop 1
	v_cndmask_b32_e32 v64, v64, v65, vcc
	v_sqrt_f32_e32 v65, v64
	s_nop 0
	v_add_u32_e32 v66, -1, v65
	v_add_u32_e32 v67, 1, v65
	v_fma_f32 v68, -v66, v65, v64
	v_fma_f32 v69, -v67, v65, v64
	v_cmp_ge_f32_e64 s[0:1], 0, v68
	s_nop 1
	v_cndmask_b32_e64 v65, v65, v66, s[0:1]
	v_cmp_lt_f32_e64 s[0:1], 0, v69
	s_nop 1
	v_cndmask_b32_e64 v65, v65, v67, s[0:1]
	v_mul_f32_e32 v66, 0x37800000, v65
	v_cndmask_b32_e32 v65, v65, v66, vcc
	v_cmp_class_f32_e32 vcc, v64, v226
	s_nop 1
	v_cndmask_b32_e32 v66, v65, v64, vcc
	v_div_scale_f32 v67, s[0:1], v66, v66, 1.0
	v_rcp_f32_e32 v68, v67
	v_div_scale_f32 v69, vcc, 1.0, v66, 1.0
	v_lshl_add_u64 v[64:65], s[8:9], 1, v[38:39]
	v_fma_f32 v70, -v67, v68, 1.0
	v_fmac_f32_e32 v68, v70, v68
	v_mul_f32_e32 v70, v69, v68
	v_fma_f32 v71, -v67, v70, v69
	v_fmac_f32_e32 v70, v71, v68
	v_fma_f32 v67, -v67, v70, v69
	v_div_fmas_f32 v67, v67, v68, v70
	v_div_fixup_f32 v66, v67, v66, 1.0
	v_pk_mul_f32 v[50:51], v[50:51], v[66:67] op_sel_hi:[1,0]
	v_pk_mul_f32 v[52:53], v[52:53], v[66:67] op_sel_hi:[1,0]
	v_pk_mul_f32 v[50:51], v[10:11], v[50:51]
	v_pk_mul_f32 v[52:53], v[12:13], v[52:53]
	v_cvt_pk_bf16_f32 v50, v50, v51
	v_cvt_pk_bf16_f32 v51, v52, v53
	global_store_dwordx2 v[64:65], v[50:51], off
	v_pk_mul_f32 v[50:51], v[54:55], v[66:67] op_sel_hi:[1,0]
	v_pk_mul_f32 v[48:49], v[48:49], v[66:67] op_sel_hi:[1,0]
	v_pk_mul_f32 v[50:51], v[6:7], v[50:51]
	v_pk_mul_f32 v[48:49], v[8:9], v[48:49]
	v_cvt_pk_bf16_f32 v50, v50, v51
	v_cvt_pk_bf16_f32 v51, v48, v49
	global_store_dwordx2 v[64:65], v[50:51], off offset:512
	v_pk_mul_f32 v[48:49], v[58:59], v[66:67] op_sel_hi:[1,0]
	v_pk_mul_f32 v[50:51], v[56:57], v[66:67] op_sel_hi:[1,0]
	v_pk_mul_f32 v[48:49], v[26:27], v[48:49]
	v_pk_mul_f32 v[50:51], v[28:29], v[50:51]
	v_cvt_pk_bf16_f32 v48, v48, v49
	v_cvt_pk_bf16_f32 v49, v50, v51
	global_store_dwordx2 v[64:65], v[48:49], off offset:1024
	v_pk_mul_f32 v[48:49], v[62:63], v[66:67] op_sel_hi:[1,0]
	v_pk_mul_f32 v[50:51], v[60:61], v[66:67] op_sel_hi:[1,0]
	v_pk_mul_f32 v[48:49], v[22:23], v[48:49]
	v_pk_mul_f32 v[50:51], v[24:25], v[50:51]
	v_cvt_pk_bf16_f32 v48, v48, v49
	v_cvt_pk_bf16_f32 v49, v50, v51
	global_store_dwordx2 v[64:65], v[48:49], off offset:1536
	s_branch .LBB0_810

; __device__ __forceinline__ float bf_lo(unsigned w) { return __uint_as_float(w << 16); }
; __device__ __forceinline__ float bf_hi(unsigned w) { return __uint_as_float(w & 0xffff0000u); }
; __device__ __forceinline__ void ew_phase(const Frame& F, const bf16_t* f, const float* gpost, float alpha, const float* hin, float* hout, const float* gpre, bf16_t* xn, ...
;     ...
;     for (int it_ = 0; it_ < it_n; ++it_) {
;         const int m = prow0 >= 0 ? prow0 + F.wave * 8 + it_ : F.gw + it_ * F.NGW; if (m >= T) break;
;         const u32x2* fr = (const u32x2*)(f + (size_t)m * DM) + F.lane; const f32x4* hr = (const f32x4*)(hin + (size_t)m * DM) + F.lane;
;         f32x4 fv[4], hv[4]; float s = 0.f;
; #pragma unroll
;         for (int j = 0; j < 4; ++j) { const u32x2 w = fr[64 * j]; hv[j] = in24 ? load24(h24 + (size_t)m * (DM * 3), F.lane + 64 * j) : hr[64 * j]; fv[j] = (f32x4){bf_lo(w.x), bf_hi(w.x), bf_lo(w.y), bf_hi(w.y)};
;             s += (fv[j].x * fv[j].x + fv[j].y * fv[j].y) + (fv[j].z * fv[j].z + fv[j].w * fv[j].w); }
;         const float rstd = alpha / sqrtf(wave_sum(s) * (1.f / DM) + RMS_EPS);
.LBB0_905:
	v_readlane_b32 s0, v252, 11
	s_add_i32 s6, s2, s3
	v_readlane_b32 s1, v252, 12
	s_and_b64 s[0:1], s[0:1], exec
	s_cselect_b32 s8, s6, s12
	s_cmpk_gt_i32 s8, 0x3fff
	s_mov_b64 s[0:1], -1
	s_cbranch_scc1 .LBB0_904
	s_ashr_i32 s9, s8, 31
	s_lshl_b64 s[6:7], s[8:9], 11
	s_mul_i32 s0, s8, 0xc00
	s_mul_hi_i32 s1, s8, 0xc00
	s_add_u32 s0, s13, s0
	s_addc_u32 s1, s14, s1
	v_lshl_add_u64 v[68:69], v[44:45], 0, s[6:7]
	v_lshl_add_u64 v[48:49], s[0:1], 0, v[36:37]
	v_lshl_add_u64 v[58:59], s[0:1], 0, v[38:39]
	v_lshl_add_u64 v[162:163], s[0:1], 0, v[40:41]
	v_lshl_add_u64 v[164:165], s[0:1], 0, v[42:43]
	global_load_dwordx2 v[56:57], v[68:69], off
	global_load_dwordx2 v[52:53], v[48:49], off
	global_load_dwordx2 v[54:55], v[48:49], off offset:4
	global_load_dwordx2 v[64:65], v[68:69], off offset:512
	global_load_dwordx2 v[62:63], v[58:59], off
	global_load_dwordx2 v[66:67], v[58:59], off offset:4
	global_load_dwordx2 v[72:73], v[68:69], off offset:1024
	global_load_dwordx2 v[76:77], v[162:163], off
	global_load_dwordx2 v[78:79], v[162:163], off offset:4
	global_load_dwordx2 v[80:81], v[68:69], off offset:1536
	global_load_dwordx2 v[166:167], v[164:165], off
	global_load_dwordx2 v[82:83], v[164:165], off offset:4
	s_mov_b32 s8, 0xff00
	s_add_i32 s3, s3, 1
	s_addk_i32 s12, 0x800
	s_cmp_eq_u32 s3, 8
	s_waitcnt vmcnt(10)
	v_lshrrev_b32_e32 v51, 8, v53
	s_waitcnt vmcnt(9)
	v_lshlrev_b32_e32 v0, 24, v55
	v_lshlrev_b32_e32 v35, 16, v54
	v_and_b32_e32 v51, 0xffff00, v51
	v_and_b32_sdwa v53, v52, s8 dst_sel:DWORD dst_unused:UNUSED_PAD src0_sel:WORD_1 src1_sel:DWORD
	v_lshlrev_b32_e32 v50, 8, v52
	v_or_b32_e32 v52, v0, v51
	v_or_b32_e32 v51, v35, v53
	v_and_b32_e32 v53, 0xffffff00, v55
	v_lshlrev_b32_e32 v54, 16, v56
	v_and_b32_e32 v55, 0xffff0000, v56
	v_lshlrev_b32_e32 v56, 16, v57
	v_and_b32_e32 v57, 0xffff0000, v57
	v_mul_f32_e32 v0, v57, v57
	s_waitcnt vmcnt(7)
	v_lshrrev_b32_e32 v61, 8, v63
	v_pk_fma_f32 v[90:91], v[56:57], v[56:57], v[0:1] op_sel_hi:[1,1,0]
	s_waitcnt vmcnt(6)
	v_lshlrev_b32_e32 v0, 24, v67
	v_lshlrev_b32_e32 v35, 16, v66
	v_and_b32_e32 v61, 0xffff00, v61
	v_and_b32_sdwa v63, v62, s8 dst_sel:DWORD dst_unused:UNUSED_PAD src0_sel:WORD_1 src1_sel:DWORD
	v_lshlrev_b32_e32 v60, 8, v62
	v_or_b32_e32 v62, v0, v61
	v_or_b32_e32 v61, v35, v63
	v_and_b32_e32 v63, 0xffffff00, v67
	v_lshlrev_b32_e32 v67, 16, v65
	v_lshlrev_b32_e32 v66, 16, v64
	v_and_b32_e32 v65, 0xffff0000, v65
	v_and_b32_e32 v64, 0xffff0000, v64
	v_pk_mul_f32 v[70:71], v[64:65], v[64:65]
	s_waitcnt vmcnt(5)
	v_lshlrev_b32_e32 v88, 16, v73
	v_pk_fma_f32 v[96:97], v[66:67], v[66:67], v[70:71]
	v_lshl_add_u64 v[70:71], s[0:1], 0, v[40:41]
	v_lshl_add_u64 v[68:69], s[0:1], 0, v[42:43]
	v_and_b32_e32 v89, 0xffff0000, v73
	v_lshlrev_b32_e32 v86, 16, v72
	v_and_b32_e32 v87, 0xffff0000, v72
	v_mov_b32_e32 v100, v90
	v_pk_add_f32 v[96:97], v[96:97], v[96:97] op_sel:[0,1] op_sel_hi:[1,0]
	s_waitcnt vmcnt(4)
	v_lshrrev_b32_e32 v75, 8, v77
	v_lshlrev_b32_e32 v74, 8, v76
	s_waitcnt vmcnt(3)
	v_lshlrev_b32_e32 v0, 24, v79
	v_lshlrev_b32_e32 v35, 16, v78
	v_and_b32_e32 v75, 0xffff00, v75
	v_and_b32_sdwa v76, v76, s8 dst_sel:DWORD dst_unused:UNUSED_PAD src0_sel:WORD_1 src1_sel:DWORD
	v_or_b32_e32 v78, v0, v75
	v_or_b32_e32 v75, v35, v76
	s_waitcnt vmcnt(2)
	v_lshlrev_b32_e32 v85, 16, v80
	v_mov_b32_e32 v101, v85
	v_and_b32_e32 v79, 0xffffff00, v79
	s_waitcnt vmcnt(1)
	v_lshrrev_b32_e32 v73, 8, v167
	s_waitcnt vmcnt(0)
	v_lshlrev_b32_e32 v0, 24, v83
	v_and_b32_e32 v73, 0xffff00, v73
	v_lshlrev_b32_e32 v72, 8, v166
	v_and_b32_sdwa v77, v166, s8 dst_sel:DWORD dst_unused:UNUSED_PAD src0_sel:WORD_1 src1_sel:DWORD
	v_or_b32_e32 v76, v0, v73
	v_mul_f32_e32 v0, v55, v55
	v_lshlrev_b32_e32 v35, 16, v82
	v_pk_fma_f32 v[98:99], v[54:55], v[54:55], v[0:1] op_sel_hi:[1,1,0]
	v_or_b32_e32 v73, v35, v77
	v_and_b32_e32 v77, 0xffffff00, v83
	v_and_b32_e32 v83, 0xffff0000, v80
	v_mov_b32_e32 v84, v98
	v_mul_f32_e32 v35, v83, v83
	v_pk_add_f32 v[90:91], v[98:99], v[90:91]
	v_pk_mul_f32 v[98:99], v[84:85], v[100:101]
	v_mov_b32_e32 v97, v35
	v_mov_b32_e32 v91, v99
	v_mul_f32_e32 v0, v87, v87
	v_lshlrev_b32_e32 v80, 16, v81
	v_and_b32_e32 v81, 0xffff0000, v81
	v_pk_add_f32 v[90:91], v[90:91], v[96:97]
	v_pk_fma_f32 v[96:97], v[86:87], v[86:87], v[0:1] op_sel_hi:[1,1,0]
	v_mul_f32_e32 v0, v89, v89
	v_mul_f32_e32 v82, v80, v80
	v_mul_f32_e32 v102, v81, v81
	v_pk_fma_f32 v[98:99], v[88:89], v[88:89], v[0:1] op_sel_hi:[1,1,0]
	v_and_b32_e32 v0, 64, v230
	v_mov_b32_e32 v97, v82
	v_mov_b32_e32 v99, v102
	v_add_u32_e32 v82, 64, v0
	v_xor_b32_e32 v0, 1, v230
	v_pk_add_f32 v[96:97], v[96:97], v[98:99]
	v_cmp_lt_i32_e32 vcc, v0, v82
	v_pk_add_f32 v[90:91], v[90:91], v[96:97]
	s_nop 0
	v_cndmask_b32_e32 v0, v230, v0, vcc
	v_add_f32_e32 v35, v90, v91
	v_lshlrev_b32_e32 v0, 2, v0
	ds_bpermute_b32 v84, v0, v35
	s_waitcnt lgkmcnt(0)
	v_add_f32_e32 v84, v35, v84
	v_xor_b32_e32 v35, 2, v230
	v_cmp_lt_i32_e32 vcc, v35, v82
	s_nop 1
	v_cndmask_b32_e32 v35, v230, v35, vcc
	v_lshlrev_b32_e32 v35, 2, v35
	ds_bpermute_b32 v90, v35, v84
	s_waitcnt lgkmcnt(0)
	v_add_f32_e32 v90, v84, v90
	v_xor_b32_e32 v84, 4, v230
	v_cmp_lt_i32_e32 vcc, v84, v82
	s_nop 1
	v_cndmask_b32_e32 v84, v230, v84, vcc
	v_lshlrev_b32_e32 v84, 2, v84
	ds_bpermute_b32 v91, v84, v90
	s_waitcnt lgkmcnt(0)
	v_add_f32_e32 v91, v90, v91
	v_xor_b32_e32 v90, 8, v230
	v_cmp_lt_i32_e32 vcc, v90, v82
	s_nop 1
	v_cndmask_b32_e32 v90, v230, v90, vcc
	v_lshlrev_b32_e32 v90, 2, v90
	ds_bpermute_b32 v96, v90, v91
	s_waitcnt lgkmcnt(0)
	v_add_f32_e32 v91, v91, v96
	v_xor_b32_e32 v96, 16, v230
	v_cmp_lt_i32_e32 vcc, v96, v82
	s_nop 1
	v_cndmask_b32_e32 v96, v230, v96, vcc
	v_lshlrev_b32_e32 v97, 2, v96
	ds_bpermute_b32 v96, v97, v91
	s_waitcnt lgkmcnt(0)
; __device__ __forceinline__ void ew_phase(const Frame& F, const bf16_t* f, const float* gpost, float alpha, const float* hin, float* hout, const float* gpre, bf16_t* xn, ...
;     ...
;         const float rstd = alpha / sqrtf(wave_sum(s) * (1.f / DM) + RMS_EPS);
;         float s2 = 0.f; f32x4* ho = (f32x4*)(hout + (size_t)m * DM) + F.lane;
; #pragma unroll
;         for (int j = 0; j < 4; ++j) { hv[j] = hv[j] + fv[j] * rstd * gp[j]; if (out24) store24(h24 + (size_t)m * (DM * 3), F.lane + 64 * j, hv[j]); else ho[64 * j] = hv[j]; s2 += (hv[j].x * hv[j].x + hv[j].y * hv[j].y) + (hv[j].z * hv[j].z + hv[j].w * hv[j].w); }
;         if (gpre) {
;             const float r2 = 1.0f / sqrtf(wave_sum(s2) * (1.f / DM) + RMS_EPS);
	v_add_f32_e32 v91, v91, v96
	v_xor_b32_e32 v96, 32, v230
	v_cmp_lt_i32_e32 vcc, v96, v82
	s_nop 1
	v_cndmask_b32_e32 v82, v230, v96, vcc
	v_lshlrev_b32_e32 v100, 2, v82
	ds_bpermute_b32 v82, v100, v91
	s_waitcnt lgkmcnt(0)
	v_add_f32_e32 v82, v91, v82
	v_fmamk_f32 v82, v82, 0x3a800000, v225
	v_cmp_gt_f32_e32 vcc, s18, v82
	v_mul_f32_e32 v91, 0x4f800000, v82
	s_nop 0
	v_cndmask_b32_e32 v82, v82, v91, vcc
	v_sqrt_f32_e32 v91, v82
	s_nop 0
	v_add_u32_e32 v96, -1, v91
	v_fma_f32 v98, -v96, v91, v82
	v_cmp_ge_f32_e64 s[0:1], 0, v98
	v_add_u32_e32 v98, 1, v91
	s_nop 0
	v_cndmask_b32_e64 v96, v91, v96, s[0:1]
	v_fma_f32 v91, -v98, v91, v82
	v_cmp_lt_f32_e64 s[0:1], 0, v91
	s_nop 1
	v_cndmask_b32_e64 v91, v96, v98, s[0:1]
	v_mul_f32_e32 v96, 0x37800000, v91
	v_cndmask_b32_e32 v91, v91, v96, vcc
	v_cmp_class_f32_e32 vcc, v82, v226
	s_nop 1
	v_cndmask_b32_e32 v82, v91, v82, vcc
	v_div_scale_f32 v91, s[0:1], v82, v82, 0.5
	v_rcp_f32_e32 v96, v91
	s_mov_b32 s0, 0x7060503
	v_fma_f32 v98, -v91, v96, 1.0
	v_fmac_f32_e32 v96, v98, v96
	v_div_scale_f32 v98, vcc, 0.5, v82, 0.5
	v_mul_f32_e32 v99, v98, v96
	v_fma_f32 v101, -v91, v99, v98
	v_fmac_f32_e32 v99, v101, v96
	v_fma_f32 v91, -v91, v99, v98
	v_div_fmas_f32 v91, v91, v96, v99
	v_div_fixup_f32 v96, v91, v82, 0.5
	v_pk_mul_f32 v[54:55], v[96:97], v[54:55] op_sel_hi:[0,1]
	v_pk_mul_f32 v[56:57], v[96:97], v[56:57] op_sel_hi:[0,1]
	v_pk_fma_f32 v[52:53], v[4:5], v[56:57], v[52:53]
	v_pk_fma_f32 v[50:51], v[2:3], v[54:55], v[50:51]
	v_bfe_u32 v57, v52, 8, 1
	v_bfe_u32 v55, v51, 8, 1
	v_bfe_u32 v54, v50, 8, 1
	v_add3_u32 v55, v51, v55, s15
	v_add3_u32 v57, v52, v57, s15
	v_bfe_u32 v91, v53, 8, 1
	v_add3_u32 v54, v50, v54, s15
	v_lshrrev_b32_e32 v56, 8, v55
	v_lshrrev_b32_e32 v82, 8, v57
	v_add3_u32 v91, v53, v91, s15
	v_alignbit_b32 v54, v56, v54, 8
	v_alignbit_b32 v55, v82, v55, 16
	v_perm_b32 v56, v91, v57, s0
	global_store_dwordx3 v[48:49], v[54:56], off
	v_pk_mul_f32 v[48:49], v[52:53], v[52:53]
	v_mov_b32_e32 v82, v85
	v_pk_mul_f32 v[54:55], v[50:51], v[50:51]
	s_nop 0
	v_pk_mov_b32 v[56:57], v[54:55], v[48:49] op_sel:[1,0]
	v_mov_b32_e32 v55, v49
	v_pk_add_f32 v[48:49], v[54:55], v[56:57]
	s_nop 0
	v_pk_add_f32 v[98:99], v[48:49], v[48:49] op_sel_hi:[0,1]
	v_mov_b32_e32 v48, v66
	v_mov_b32_e32 v49, v64
	v_mov_b32_e32 v64, v67
	v_pk_mul_f32 v[54:55], v[96:97], v[48:49] op_sel_hi:[0,1]
	v_pk_mul_f32 v[48:49], v[96:97], v[64:65] op_sel_hi:[0,1]
	v_pk_fma_f32 v[48:49], v[8:9], v[48:49], v[62:63]
	v_pk_fma_f32 v[54:55], v[6:7], v[54:55], v[60:61]
	v_bfe_u32 v61, v48, 8, 1
	v_bfe_u32 v57, v55, 8, 1
	v_bfe_u32 v56, v54, 8, 1
	v_add3_u32 v57, v55, v57, s15
	v_add3_u32 v62, v48, v61, s15
	v_bfe_u32 v63, v49, 8, 1
	v_add3_u32 v56, v54, v56, s15
	v_lshrrev_b32_e32 v60, 8, v57
	v_lshrrev_b32_e32 v61, 8, v62
	v_add3_u32 v63, v49, v63, s15
	v_alignbit_b32 v60, v60, v56, 8
	v_alignbit_b32 v61, v61, v57, 16
	v_perm_b32 v62, v63, v62, s0
	global_store_dwordx3 v[58:59], v[60:62], off
	v_pk_mul_f32 v[56:57], v[48:49], v[48:49]
	v_pk_mul_f32 v[58:59], v[54:55], v[54:55]
	s_nop 0
	v_pk_mov_b32 v[60:61], v[58:59], v[56:57] op_sel:[1,0]
	v_mov_b32_e32 v59, v57
	v_pk_add_f32 v[56:57], v[58:59], v[60:61]
	v_pk_mul_f32 v[58:59], v[96:97], v[86:87] op_sel_hi:[0,1]
	v_pk_add_f32 v[66:67], v[56:57], v[56:57] op_sel_hi:[0,1]
	v_pk_mul_f32 v[56:57], v[96:97], v[88:89] op_sel_hi:[0,1]
	v_pk_fma_f32 v[56:57], v[20:21], v[56:57], v[78:79]
	v_pk_fma_f32 v[58:59], v[18:19], v[58:59], v[74:75]
	v_bfe_u32 v63, v56, 8, 1
	v_bfe_u32 v61, v59, 8, 1
	v_bfe_u32 v60, v58, 8, 1
	v_add3_u32 v61, v59, v61, s15
	v_add3_u32 v63, v56, v63, s15
	v_bfe_u32 v65, v57, 8, 1
	v_add3_u32 v60, v58, v60, s15
	v_lshrrev_b32_e32 v62, 8, v61
	v_lshrrev_b32_e32 v64, 8, v63
	v_add3_u32 v65, v57, v65, s15
	v_alignbit_b32 v60, v62, v60, 8
	v_alignbit_b32 v61, v64, v61, 16
	v_perm_b32 v62, v65, v63, s0
	global_store_dwordx3 v[70:71], v[60:62], off
	s_nop 1
	v_mul_f32_e32 v60, v58, v58
	v_pk_fma_f32 v[70:71], v[58:59], v[58:59], v[60:61] op_sel_hi:[1,1,0]
	v_mul_f32_e32 v60, v56, v56
	v_pk_fma_f32 v[74:75], v[56:57], v[56:57], v[60:61] op_sel_hi:[1,1,0]
	v_pk_mul_f32 v[62:63], v[82:83], v[96:97] op_sel_hi:[1,0]
	v_pk_mul_f32 v[60:61], v[80:81], v[96:97] op_sel_hi:[1,0]
	v_pk_fma_f32 v[62:63], v[22:23], v[62:63], v[72:73]
	v_pk_fma_f32 v[60:61], v[24:25], v[60:61], v[76:77]
	v_bfe_u32 v65, v63, 8, 1
	v_bfe_u32 v70, v60, 8, 1
	v_bfe_u32 v64, v62, 8, 1
	v_add3_u32 v65, v63, v65, s15
	v_add3_u32 v70, v60, v70, s15
	v_bfe_u32 v73, v61, 8, 1
	v_add3_u32 v64, v62, v64, s15
	v_lshrrev_b32_e32 v66, 8, v65
	v_lshrrev_b32_e32 v72, 8, v70
	v_add3_u32 v73, v61, v73, s15
	v_alignbit_b32 v64, v66, v64, 8
	v_alignbit_b32 v65, v72, v65, 16
	v_perm_b32 v66, v73, v70, s0
	global_store_dwordx3 v[68:69], v[64:66], off
	v_mul_f32_e32 v70, v62, v62
	v_mul_f32_e32 v74, v63, v63
	v_mul_f32_e32 v98, v61, v61
	v_mul_f32_e32 v66, v60, v60
	v_pk_add_f32 v[64:65], v[70:71], v[74:75]
	v_pk_add_f32 v[66:67], v[98:99], v[66:67]
	s_nop 0
	v_pk_add_f32 v[64:65], v[64:65], v[66:67]
	s_nop 0
	v_add_f32_e32 v64, v64, v65
	ds_bpermute_b32 v0, v0, v64
	s_waitcnt lgkmcnt(0)
; __device__ __forceinline__ unsigned cvt_pk_bf16(float lo, float hi) { f32x2 v = {lo, hi}; bf16x2_t b = __builtin_convertvector(v, bf16x2_t); return __builtin_bit_cast(unsigned, b); }
; __device__ __forceinline__ void ew_phase(const Frame& F, const bf16_t* f, const float* gpost, float alpha, const float* hin, float* hout, const float* gpre, bf16_t* xn, ...
;     ...
;             const float r2 = 1.0f / sqrtf(wave_sum(s2) * (1.f / DM) + RMS_EPS);
;             u32x2* o8 = (u32x2*)(xn + (size_t)m * DM) + F.lane;
; #pragma unroll
;             for (int j = 0; j < 4; ++j) { hv[j] = hv[j] * r2 * gq[j]; u32x2 w; w.x = cvt_pk_bf16(hv[j].x, hv[j].y); w.y = cvt_pk_bf16(hv[j].z, hv[j].w); o8[64 * j] = w; }
	v_add_f32_e32 v0, v64, v0
	ds_bpermute_b32 v35, v35, v0
	s_waitcnt lgkmcnt(0)
	v_add_f32_e32 v0, v0, v35
	ds_bpermute_b32 v35, v84, v0
	s_waitcnt lgkmcnt(0)
	v_add_f32_e32 v0, v0, v35
	ds_bpermute_b32 v35, v90, v0
	s_waitcnt lgkmcnt(0)
	v_add_f32_e32 v0, v0, v35
	ds_bpermute_b32 v35, v97, v0
	s_waitcnt lgkmcnt(0)
	v_add_f32_e32 v0, v0, v35
	ds_bpermute_b32 v35, v100, v0
	s_waitcnt lgkmcnt(0)
	v_add_f32_e32 v0, v0, v35
	v_fmamk_f32 v0, v0, 0x3a800000, v225
	v_cmp_gt_f32_e32 vcc, s18, v0
	v_mul_f32_e32 v35, 0x4f800000, v0
	s_nop 0
	v_cndmask_b32_e32 v0, v0, v35, vcc
	v_sqrt_f32_e32 v35, v0
	s_nop 0
	v_add_u32_e32 v64, -1, v35
	v_fma_f32 v65, -v64, v35, v0
	v_cmp_ge_f32_e64 s[0:1], 0, v65
	v_add_u32_e32 v65, 1, v35
	s_nop 0
	v_cndmask_b32_e64 v64, v35, v64, s[0:1]
	v_fma_f32 v35, -v65, v35, v0
	v_cmp_lt_f32_e64 s[0:1], 0, v35
	s_nop 1
	v_cndmask_b32_e64 v35, v64, v65, s[0:1]
	v_mul_f32_e32 v64, 0x37800000, v35
	v_cndmask_b32_e32 v35, v35, v64, vcc
	v_cmp_class_f32_e32 vcc, v0, v226
	s_nop 1
	v_cndmask_b32_e32 v0, v35, v0, vcc
	v_div_scale_f32 v35, s[0:1], v0, v0, 1.0
	v_rcp_f32_e32 v64, v35
	s_cselect_b64 s[0:1], -1, 0
	v_fma_f32 v65, -v35, v64, 1.0
	v_fmac_f32_e32 v64, v65, v64
	v_div_scale_f32 v65, vcc, 1.0, v0, 1.0
	v_mul_f32_e32 v66, v65, v64
	v_fma_f32 v67, -v35, v66, v65
	v_fmac_f32_e32 v66, v67, v64
	v_fma_f32 v35, -v35, v66, v65
	v_div_fmas_f32 v35, v35, v64, v66
	v_div_fixup_f32 v0, v35, v0, 1.0
	v_pk_mul_f32 v[50:51], v[50:51], v[0:1] op_sel_hi:[1,0]
	v_pk_mul_f32 v[52:53], v[52:53], v[0:1] op_sel_hi:[1,0]
	v_pk_mul_f32 v[50:51], v[10:11], v[50:51]
	v_pk_mul_f32 v[52:53], v[12:13], v[52:53]
	v_lshl_add_u64 v[64:65], v[46:47], 0, s[6:7]
	v_cvt_pk_bf16_f32 v50, v50, v51
	v_cvt_pk_bf16_f32 v51, v52, v53
	global_store_dwordx2 v[64:65], v[50:51], off
	v_pk_mul_f32 v[50:51], v[54:55], v[0:1] op_sel_hi:[1,0]
	v_pk_mul_f32 v[48:49], v[48:49], v[0:1] op_sel_hi:[1,0]
	v_pk_mul_f32 v[50:51], v[14:15], v[50:51]
	v_pk_mul_f32 v[48:49], v[16:17], v[48:49]
	v_cvt_pk_bf16_f32 v50, v50, v51
	v_cvt_pk_bf16_f32 v51, v48, v49
	global_store_dwordx2 v[64:65], v[50:51], off offset:512
	v_pk_mul_f32 v[48:49], v[58:59], v[0:1] op_sel_hi:[1,0]
	v_pk_mul_f32 v[50:51], v[56:57], v[0:1] op_sel_hi:[1,0]
	v_pk_mul_f32 v[48:49], v[26:27], v[48:49]
	v_pk_mul_f32 v[50:51], v[28:29], v[50:51]
	v_cvt_pk_bf16_f32 v48, v48, v49
	v_cvt_pk_bf16_f32 v49, v50, v51
	global_store_dwordx2 v[64:65], v[48:49], off offset:1024
	v_pk_mul_f32 v[48:49], v[62:63], v[0:1] op_sel_hi:[1,0]
	v_pk_mul_f32 v[50:51], v[60:61], v[0:1] op_sel_hi:[1,0]
	v_pk_mul_f32 v[48:49], v[30:31], v[48:49]
	v_pk_mul_f32 v[50:51], v[32:33], v[50:51]
	v_cvt_pk_bf16_f32 v48, v48, v49
	v_cvt_pk_bf16_f32 v49, v50, v51
	global_store_dwordx2 v[64:65], v[48:49], off offset:1536
	s_branch .LBB0_904
